# residual GEMM epilogues (P3/P5/P11): the 14 residual loads of slices 1..7 issued behind slice 0's, in-slice loads become moves, per-slice vmcnt waits removed
# speedup vs baseline: 1.0398x; 1.0034x over previous
.LBB0_370:
	v_lshl_add_u32 v146, s36, 8, v1
	v_ashrrev_i32_e32 v147, 31, v146
	v_lshl_or_b32 v150, s46, 8, v153
	v_lshlrev_b64 v[148:149], 11, v[146:147]
	v_ashrrev_i32_e32 v151, 31, v150
	v_lshl_add_u64 v[148:149], s[78:79], 0, v[148:149]
	v_lshl_add_u64 v[148:149], v[150:151], 1, v[148:149]
	global_load_dwordx4 v[160:163], v[148:149], off
	global_load_dwordx4 v[164:167], v[148:149], off offset:256
	s_mov_b32 s95, 0
	s_mov_b32 s94, 0x8000
	v_lshl_add_u64 v[244:245], v[148:149], 0, s[94:95]
	global_load_dwordx4 v[176:179], v[244:245], off
	global_load_dwordx4 v[180:183], v[244:245], off offset:256
	s_mov_b32 s94, 0x10000
	v_lshl_add_u64 v[246:247], v[148:149], 0, s[94:95]
	global_load_dwordx4 v[184:187], v[246:247], off
	global_load_dwordx4 v[188:191], v[246:247], off offset:256
	s_mov_b32 s94, 0x18000
	v_lshl_add_u64 v[244:245], v[148:149], 0, s[94:95]
	global_load_dwordx4 v[192:195], v[244:245], off
	global_load_dwordx4 v[200:203], v[244:245], off offset:256
	s_mov_b32 s94, 0x40000
	v_lshl_add_u64 v[246:247], v[148:149], 0, s[94:95]
	global_load_dwordx4 v[204:207], v[246:247], off
	global_load_dwordx4 v[208:211], v[246:247], off offset:256
	s_mov_b32 s94, 0x48000
	v_lshl_add_u64 v[244:245], v[148:149], 0, s[94:95]
	global_load_dwordx4 v[212:215], v[244:245], off
	global_load_dwordx4 v[216:219], v[244:245], off offset:256
	s_mov_b32 s94, 0x50000
	v_lshl_add_u64 v[246:247], v[148:149], 0, s[94:95]
	global_load_dwordx4 v[228:231], v[246:247], off
	global_load_dwordx4 v[232:235], v[246:247], off offset:256
	s_mov_b32 s94, 0x58000
	v_lshl_add_u64 v[244:245], v[148:149], 0, s[94:95]
	global_load_dwordx4 v[236:239], v[244:245], off
	global_load_dwordx4 v[240:243], v[244:245], off offset:256
	v_and_b32_e32 v159, 64, v157
	v_xor_b32_e32 v158, 16, v157
	v_add_u32_e32 v159, 64, v159
	v_xor_b32_e32 v168, 32, v157
	v_cmp_lt_i32_e32 vcc, v158, v159
	s_waitcnt vmcnt(0)
	v_and_b32_e32 v169, 0xffff0000, v160
	v_cndmask_b32_e32 v158, v157, v158, vcc
	v_cmp_lt_i32_e32 vcc, v168, v159
	v_lshlrev_b32_e32 v172, 16, v164
	v_and_b32_e32 v173, 0xffff0000, v164
	v_cndmask_b32_e32 v159, v157, v168, vcc
	v_lshlrev_b32_e32 v168, 16, v160
	v_lshlrev_b32_e32 v160, 16, v161
	v_and_b32_e32 v161, 0xffff0000, v161
	v_lshlrev_b32_e32 v164, 16, v165
	v_and_b32_e32 v165, 0xffff0000, v165
	v_lshlrev_b32_e32 v170, 16, v162
	v_and_b32_e32 v171, 0xffff0000, v162
	v_lshlrev_b32_e32 v162, 16, v163
	v_and_b32_e32 v163, 0xffff0000, v163
	v_lshlrev_b32_e32 v174, 16, v166
	v_and_b32_e32 v175, 0xffff0000, v166
	v_lshlrev_b32_e32 v166, 16, v167
	v_and_b32_e32 v167, 0xffff0000, v167
	v_pk_add_f32 v[128:129], v[128:129], v[160:161]
	v_pk_add_f32 v[126:127], v[126:127], v[168:169]
	v_pk_add_f32 v[120:121], v[120:121], v[164:165]
	v_pk_add_f32 v[118:119], v[118:119], v[172:173]
	v_pk_add_f32 v[124:125], v[124:125], v[162:163]
	v_pk_add_f32 v[122:123], v[122:123], v[170:171]
	v_pk_add_f32 v[160:161], v[116:117], v[166:167]
	v_pk_add_f32 v[162:163], v[114:115], v[174:175]
	v_mul_f32_e32 v116, v127, v127
	v_mul_f32_e32 v117, v129, v129
	v_mul_f32_e32 v166, v119, v119
	v_mul_f32_e32 v167, v121, v121
	v_cvt_pk_bf16_f32 v114, v126, v127
	v_mul_f32_e32 v127, v123, v123
	v_mul_f32_e32 v165, v163, v163
	v_fmac_f32_e32 v116, v126, v126
	v_fmac_f32_e32 v117, v128, v128
	v_fmac_f32_e32 v166, v118, v118
	v_fmac_f32_e32 v167, v120, v120
	v_cvt_pk_bf16_f32 v115, v128, v129
	v_mul_f32_e32 v129, v125, v125
	v_mul_f32_e32 v164, v161, v161
	v_fmac_f32_e32 v127, v122, v122
	v_fmac_f32_e32 v165, v162, v162
	v_add_f32_e32 v116, v116, v117
	v_add_f32_e32 v117, v166, v167
	v_fmac_f32_e32 v129, v124, v124
	v_fmac_f32_e32 v164, v160, v160
	v_add_f32_e32 v116, v127, v116
	v_add_f32_e32 v117, v165, v117
	v_add_f32_e32 v116, v129, v116
	v_add_f32_e32 v117, v164, v117
	v_lshlrev_b32_e32 v158, 2, v158
	v_add_f32_e32 v126, v116, v117
	ds_bpermute_b32 v127, v158, v126
	v_cvt_pk_bf16_f32 v116, v122, v123
	v_cvt_pk_bf16_f32 v117, v124, v125
	global_store_dwordx4 v[148:149], v[114:117], off
	v_cvt_pk_bf16_f32 v118, v118, v119
	v_cvt_pk_bf16_f32 v119, v120, v121
	s_waitcnt lgkmcnt(0)
	v_add_f32_e32 v115, v126, v127
	v_lshlrev_b32_e32 v114, 2, v159
	ds_bpermute_b32 v116, v114, v115
	v_cvt_pk_bf16_f32 v120, v162, v163
	v_cvt_pk_bf16_f32 v121, v160, v161
	global_store_dwordx4 v[148:149], v[118:121], off offset:256
	s_and_saveexec_b64 s[12:13], s[2:3]
	s_cbranch_execz .LBB0_372
	v_lshl_add_u64 v[118:119], v[146:147], 2, s[72:73]
	s_waitcnt lgkmcnt(0)
	v_add_f32_e32 v115, v115, v116
	global_atomic_add_f32 v[118:119], v115, off
.LBB0_372:
	s_or_b64 exec, exec, s[12:13]
	s_waitcnt lgkmcnt(0)
	v_or_b32_e32 v116, 16, v146
	v_ashrrev_i32_e32 v117, 31, v116
	v_lshlrev_b64 v[116:117], 11, v[116:117]
	v_lshl_add_u64 v[116:117], s[78:79], 0, v[116:117]
	v_lshl_add_u64 v[124:125], v[150:151], 1, v[116:117]
	v_mov_b32_e32 v116, v176
	v_mov_b32_e32 v117, v177
	v_mov_b32_e32 v118, v178
	v_mov_b32_e32 v119, v179
	v_mov_b32_e32 v120, v180
	v_mov_b32_e32 v121, v181
	v_mov_b32_e32 v122, v182
	v_mov_b32_e32 v123, v183
	v_lshlrev_b32_e32 v126, 16, v116
	v_and_b32_e32 v127, 0xffff0000, v116
	v_lshlrev_b32_e32 v116, 16, v117
	v_and_b32_e32 v117, 0xffff0000, v117
	v_lshlrev_b32_e32 v160, 16, v120
	v_and_b32_e32 v161, 0xffff0000, v120
	v_lshlrev_b32_e32 v120, 16, v121
	v_and_b32_e32 v121, 0xffff0000, v121
	v_lshlrev_b32_e32 v128, 16, v118
	v_and_b32_e32 v129, 0xffff0000, v118
	v_lshlrev_b32_e32 v118, 16, v119
	v_and_b32_e32 v119, 0xffff0000, v119
	v_lshlrev_b32_e32 v162, 16, v122
	v_and_b32_e32 v163, 0xffff0000, v122
	v_lshlrev_b32_e32 v122, 16, v123
	v_and_b32_e32 v123, 0xffff0000, v123
	v_pk_add_f32 v[112:113], v[112:113], v[116:117]
	v_pk_add_f32 v[110:111], v[110:111], v[126:127]
	v_pk_add_f32 v[104:105], v[104:105], v[120:121]
	v_pk_add_f32 v[102:103], v[102:103], v[160:161]
	v_pk_add_f32 v[108:109], v[108:109], v[118:119]
	v_pk_add_f32 v[106:107], v[106:107], v[128:129]
	v_pk_add_f32 v[116:117], v[100:101], v[122:123]
	v_pk_add_f32 v[118:119], v[98:99], v[162:163]
	v_mul_f32_e32 v100, v111, v111
	v_mul_f32_e32 v101, v113, v113
	v_mul_f32_e32 v121, v103, v103
	v_mul_f32_e32 v122, v105, v105
	v_cvt_pk_bf16_f32 v98, v110, v111
	v_mul_f32_e32 v111, v107, v107
	v_mul_f32_e32 v120, v119, v119
	v_fmac_f32_e32 v100, v110, v110
	v_fmac_f32_e32 v101, v112, v112
	v_fmac_f32_e32 v121, v102, v102
	v_fmac_f32_e32 v122, v104, v104
	v_cvt_pk_bf16_f32 v99, v112, v113
	v_mul_f32_e32 v113, v109, v109
	v_mul_f32_e32 v115, v117, v117
	v_fmac_f32_e32 v111, v106, v106
	v_fmac_f32_e32 v120, v118, v118
	v_add_f32_e32 v100, v100, v101
	v_add_f32_e32 v101, v121, v122
	v_fmac_f32_e32 v113, v108, v108
	v_fmac_f32_e32 v115, v116, v116
	v_add_f32_e32 v100, v111, v100
	v_add_f32_e32 v101, v120, v101
	v_add_f32_e32 v100, v113, v100
	v_add_f32_e32 v101, v115, v101
	v_add_f32_e32 v110, v100, v101
	ds_bpermute_b32 v111, v158, v110
	v_cvt_pk_bf16_f32 v100, v106, v107
	v_cvt_pk_bf16_f32 v101, v108, v109
	global_store_dwordx4 v[124:125], v[98:101], off
	s_waitcnt lgkmcnt(0)
	s_nop 0
	v_add_f32_e32 v98, v110, v111
	ds_bpermute_b32 v99, v114, v98
	v_cvt_pk_bf16_f32 v100, v102, v103
	v_cvt_pk_bf16_f32 v101, v104, v105
	v_cvt_pk_bf16_f32 v102, v118, v119
	v_cvt_pk_bf16_f32 v103, v116, v117
	global_store_dwordx4 v[124:125], v[100:103], off offset:256
	s_and_saveexec_b64 s[12:13], s[2:3]
	s_cbranch_execz .LBB0_374
	v_lshl_add_u64 v[100:101], v[146:147], 2, s[72:73]
	s_waitcnt lgkmcnt(0)
	v_add_f32_e32 v98, v98, v99
	global_atomic_add_f32 v[100:101], v98, off offset:64
.LBB0_374:
	s_or_b64 exec, exec, s[12:13]
	v_or_b32_e32 v98, 32, v146
	s_waitcnt lgkmcnt(0)
	v_ashrrev_i32_e32 v99, 31, v98
	v_lshlrev_b64 v[98:99], 11, v[98:99]
	v_lshl_add_u64 v[98:99], s[78:79], 0, v[98:99]
	v_lshl_add_u64 v[106:107], v[150:151], 1, v[98:99]
	v_mov_b32_e32 v98, v184
	v_mov_b32_e32 v99, v185
	v_mov_b32_e32 v100, v186
	v_mov_b32_e32 v101, v187
	v_mov_b32_e32 v102, v188
	v_mov_b32_e32 v103, v189
	v_mov_b32_e32 v104, v190
	v_mov_b32_e32 v105, v191
	v_lshlrev_b32_e32 v108, 16, v98
	v_and_b32_e32 v109, 0xffff0000, v98
	v_lshlrev_b32_e32 v98, 16, v99
	v_and_b32_e32 v99, 0xffff0000, v99
	v_lshlrev_b32_e32 v112, 16, v102
	v_and_b32_e32 v113, 0xffff0000, v102
	v_lshlrev_b32_e32 v102, 16, v103
	v_and_b32_e32 v103, 0xffff0000, v103
	v_lshlrev_b32_e32 v110, 16, v100
	v_and_b32_e32 v111, 0xffff0000, v100
	v_lshlrev_b32_e32 v100, 16, v101
	v_and_b32_e32 v101, 0xffff0000, v101
	v_lshlrev_b32_e32 v116, 16, v104
	v_and_b32_e32 v117, 0xffff0000, v104
	v_lshlrev_b32_e32 v104, 16, v105
	v_and_b32_e32 v105, 0xffff0000, v105
	v_pk_add_f32 v[96:97], v[96:97], v[98:99]
	v_pk_add_f32 v[94:95], v[94:95], v[108:109]
	v_pk_add_f32 v[88:89], v[88:89], v[102:103]
	v_pk_add_f32 v[86:87], v[86:87], v[112:113]
	v_pk_add_f32 v[92:93], v[92:93], v[100:101]
	v_pk_add_f32 v[90:91], v[90:91], v[110:111]
	v_pk_add_f32 v[98:99], v[84:85], v[104:105]
	v_pk_add_f32 v[100:101], v[82:83], v[116:117]
	v_mul_f32_e32 v84, v95, v95
	v_mul_f32_e32 v85, v97, v97
	v_mul_f32_e32 v104, v87, v87
	v_mul_f32_e32 v105, v89, v89
	v_cvt_pk_bf16_f32 v82, v94, v95
	v_mul_f32_e32 v95, v91, v91
	v_mul_f32_e32 v103, v101, v101
	v_fmac_f32_e32 v84, v94, v94
	v_fmac_f32_e32 v85, v96, v96
	v_fmac_f32_e32 v104, v86, v86
	v_fmac_f32_e32 v105, v88, v88
	v_cvt_pk_bf16_f32 v83, v96, v97
	v_mul_f32_e32 v97, v93, v93
	v_mul_f32_e32 v102, v99, v99
	v_fmac_f32_e32 v95, v90, v90
	v_fmac_f32_e32 v103, v100, v100
	v_add_f32_e32 v84, v84, v85
	v_add_f32_e32 v85, v104, v105
	v_fmac_f32_e32 v97, v92, v92
	v_fmac_f32_e32 v102, v98, v98
	v_add_f32_e32 v84, v95, v84
	v_add_f32_e32 v85, v103, v85
	v_add_f32_e32 v84, v97, v84
	v_add_f32_e32 v85, v102, v85
	v_add_f32_e32 v94, v84, v85
	ds_bpermute_b32 v95, v158, v94
	v_cvt_pk_bf16_f32 v84, v90, v91
	v_cvt_pk_bf16_f32 v85, v92, v93
	global_store_dwordx4 v[106:107], v[82:85], off
	s_waitcnt lgkmcnt(0)
	s_nop 0
	v_add_f32_e32 v82, v94, v95
	ds_bpermute_b32 v83, v114, v82
	v_cvt_pk_bf16_f32 v84, v86, v87
	v_cvt_pk_bf16_f32 v85, v88, v89
	v_cvt_pk_bf16_f32 v86, v100, v101
	v_cvt_pk_bf16_f32 v87, v98, v99
	global_store_dwordx4 v[106:107], v[84:87], off offset:256
	s_and_saveexec_b64 s[12:13], s[2:3]
	s_cbranch_execz .LBB0_376
	v_lshl_add_u64 v[84:85], v[146:147], 2, s[72:73]
	s_waitcnt lgkmcnt(0)
	v_add_f32_e32 v82, v82, v83
	global_atomic_add_f32 v[84:85], v82, off offset:128
.LBB0_376:
	s_or_b64 exec, exec, s[12:13]
	v_or_b32_e32 v82, 48, v146
	s_waitcnt lgkmcnt(0)
	v_ashrrev_i32_e32 v83, 31, v82
	v_lshlrev_b64 v[82:83], 11, v[82:83]
	v_lshl_add_u64 v[82:83], s[78:79], 0, v[82:83]
	v_lshl_add_u64 v[90:91], v[150:151], 1, v[82:83]
	v_mov_b32_e32 v82, v192
	v_mov_b32_e32 v83, v193
	v_mov_b32_e32 v84, v194
	v_mov_b32_e32 v85, v195
	v_mov_b32_e32 v86, v200
	v_mov_b32_e32 v87, v201
	v_mov_b32_e32 v88, v202
	v_mov_b32_e32 v89, v203
	v_lshlrev_b32_e32 v92, 16, v82
	v_and_b32_e32 v93, 0xffff0000, v82
	v_lshlrev_b32_e32 v82, 16, v83
	v_and_b32_e32 v83, 0xffff0000, v83
	v_lshlrev_b32_e32 v96, 16, v86
	v_and_b32_e32 v97, 0xffff0000, v86
	v_lshlrev_b32_e32 v86, 16, v87
	v_and_b32_e32 v87, 0xffff0000, v87
	v_lshlrev_b32_e32 v94, 16, v84
	v_and_b32_e32 v95, 0xffff0000, v84
	v_lshlrev_b32_e32 v84, 16, v85
	v_and_b32_e32 v85, 0xffff0000, v85
	v_lshlrev_b32_e32 v98, 16, v88
	v_and_b32_e32 v99, 0xffff0000, v88
	v_lshlrev_b32_e32 v88, 16, v89
	v_and_b32_e32 v89, 0xffff0000, v89
	v_pk_add_f32 v[80:81], v[80:81], v[82:83]
	v_pk_add_f32 v[78:79], v[78:79], v[92:93]
	v_pk_add_f32 v[72:73], v[72:73], v[86:87]
	v_pk_add_f32 v[70:71], v[70:71], v[96:97]
	v_pk_add_f32 v[76:77], v[76:77], v[84:85]
	v_pk_add_f32 v[74:75], v[74:75], v[94:95]
	v_pk_add_f32 v[82:83], v[68:69], v[88:89]
	v_pk_add_f32 v[84:85], v[66:67], v[98:99]
	v_mul_f32_e32 v68, v79, v79
	v_mul_f32_e32 v69, v81, v81
	v_mul_f32_e32 v88, v71, v71
	v_mul_f32_e32 v89, v73, v73
	v_cvt_pk_bf16_f32 v66, v78, v79
	v_mul_f32_e32 v79, v75, v75
	v_mul_f32_e32 v87, v85, v85
	v_fmac_f32_e32 v68, v78, v78
	v_fmac_f32_e32 v69, v80, v80
	v_fmac_f32_e32 v88, v70, v70
	v_fmac_f32_e32 v89, v72, v72
	v_cvt_pk_bf16_f32 v67, v80, v81
	v_mul_f32_e32 v81, v77, v77
	v_mul_f32_e32 v86, v83, v83
	v_fmac_f32_e32 v79, v74, v74
	v_fmac_f32_e32 v87, v84, v84
	v_add_f32_e32 v68, v68, v69
	v_add_f32_e32 v69, v88, v89
	v_fmac_f32_e32 v81, v76, v76
	v_fmac_f32_e32 v86, v82, v82
	v_add_f32_e32 v68, v79, v68
	v_add_f32_e32 v69, v87, v69
	v_add_f32_e32 v68, v81, v68
	v_add_f32_e32 v69, v86, v69
	v_add_f32_e32 v78, v68, v69
	ds_bpermute_b32 v79, v158, v78
	v_cvt_pk_bf16_f32 v68, v74, v75
	v_cvt_pk_bf16_f32 v69, v76, v77
	global_store_dwordx4 v[90:91], v[66:69], off
	s_waitcnt lgkmcnt(0)
	s_nop 0
	v_add_f32_e32 v66, v78, v79
	ds_bpermute_b32 v67, v114, v66
	v_cvt_pk_bf16_f32 v68, v70, v71
	v_cvt_pk_bf16_f32 v69, v72, v73
	v_cvt_pk_bf16_f32 v70, v84, v85
	v_cvt_pk_bf16_f32 v71, v82, v83
	global_store_dwordx4 v[90:91], v[68:71], off offset:256
	s_and_saveexec_b64 s[12:13], s[2:3]
	s_cbranch_execz .LBB0_378
	v_lshl_add_u64 v[68:69], v[146:147], 2, s[72:73]
	s_waitcnt lgkmcnt(0)
	v_add_f32_e32 v66, v66, v67
	global_atomic_add_f32 v[68:69], v66, off offset:192
.LBB0_378:
	s_or_b64 exec, exec, s[12:13]
	v_add_co_u32_e32 v74, vcc, 0x40000, v148
	v_lshl_add_u64 v[76:77], v[148:149], 0, s[6:7]
	s_nop 0
	v_addc_co_u32_e32 v75, vcc, 0, v149, vcc
	s_waitcnt lgkmcnt(0)
	v_mov_b32_e32 v66, v204
	v_mov_b32_e32 v67, v205
	v_mov_b32_e32 v68, v206
	v_mov_b32_e32 v69, v207
	v_mov_b32_e32 v70, v208
	v_mov_b32_e32 v71, v209
	v_mov_b32_e32 v72, v210
	v_mov_b32_e32 v73, v211
	v_lshlrev_b32_e32 v78, 16, v66
	v_and_b32_e32 v79, 0xffff0000, v66
	v_lshlrev_b32_e32 v66, 16, v67
	v_and_b32_e32 v67, 0xffff0000, v67
	v_lshlrev_b32_e32 v82, 16, v70
	v_and_b32_e32 v83, 0xffff0000, v70
	v_lshlrev_b32_e32 v70, 16, v71
	v_and_b32_e32 v71, 0xffff0000, v71
	v_lshlrev_b32_e32 v80, 16, v68
	v_and_b32_e32 v81, 0xffff0000, v68
	v_lshlrev_b32_e32 v68, 16, v69
	v_and_b32_e32 v69, 0xffff0000, v69
	v_lshlrev_b32_e32 v84, 16, v72
	v_and_b32_e32 v85, 0xffff0000, v72
	v_lshlrev_b32_e32 v72, 16, v73
	v_and_b32_e32 v73, 0xffff0000, v73
	v_pk_add_f32 v[64:65], v[64:65], v[66:67]
	v_pk_add_f32 v[62:63], v[62:63], v[78:79]
	v_pk_add_f32 v[56:57], v[56:57], v[70:71]
	v_pk_add_f32 v[54:55], v[54:55], v[82:83]
	v_pk_add_f32 v[60:61], v[60:61], v[68:69]
	v_pk_add_f32 v[58:59], v[58:59], v[80:81]
	v_pk_add_f32 v[66:67], v[52:53], v[72:73]
	v_pk_add_f32 v[68:69], v[50:51], v[84:85]
	v_mul_f32_e32 v52, v63, v63
	v_mul_f32_e32 v53, v65, v65
	v_mul_f32_e32 v72, v55, v55
	v_mul_f32_e32 v73, v57, v57
	v_cvt_pk_bf16_f32 v50, v62, v63
	v_mul_f32_e32 v63, v59, v59
	v_mul_f32_e32 v71, v69, v69
	v_fmac_f32_e32 v52, v62, v62
	v_fmac_f32_e32 v53, v64, v64
	v_fmac_f32_e32 v72, v54, v54
	v_fmac_f32_e32 v73, v56, v56
	v_cvt_pk_bf16_f32 v51, v64, v65
	v_mul_f32_e32 v65, v61, v61
	v_mul_f32_e32 v70, v67, v67
	v_fmac_f32_e32 v63, v58, v58
	v_fmac_f32_e32 v71, v68, v68
	v_add_f32_e32 v52, v52, v53
	v_add_f32_e32 v53, v72, v73
	v_fmac_f32_e32 v65, v60, v60
	v_fmac_f32_e32 v70, v66, v66
	v_add_f32_e32 v52, v63, v52
	v_add_f32_e32 v53, v71, v53
	v_add_f32_e32 v52, v65, v52
	v_add_f32_e32 v53, v70, v53
	v_add_f32_e32 v62, v52, v53
	ds_bpermute_b32 v63, v158, v62
	v_cvt_pk_bf16_f32 v52, v58, v59
	v_cvt_pk_bf16_f32 v53, v60, v61
	global_store_dwordx4 v[74:75], v[50:53], off
	s_waitcnt lgkmcnt(0)
	s_nop 0
	v_add_f32_e32 v50, v62, v63
	ds_bpermute_b32 v51, v114, v50
	v_cvt_pk_bf16_f32 v52, v54, v55
	v_cvt_pk_bf16_f32 v53, v56, v57
	v_cvt_pk_bf16_f32 v54, v68, v69
	v_cvt_pk_bf16_f32 v55, v66, v67
	global_store_dwordx4 v[76:77], v[52:55], off offset:256
	s_and_saveexec_b64 s[12:13], s[2:3]
	s_cbranch_execz .LBB0_380
	v_lshl_add_u64 v[52:53], v[146:147], 2, s[72:73]
	s_waitcnt lgkmcnt(0)
	v_add_f32_e32 v50, v50, v51
	global_atomic_add_f32 v[52:53], v50, off offset:512
.LBB0_380:
	s_or_b64 exec, exec, s[12:13]
	v_add_co_u32_e32 v58, vcc, 0x48000, v148
	v_lshl_add_u64 v[60:61], v[148:149], 0, s[16:17]
	s_nop 0
	v_addc_co_u32_e32 v59, vcc, 0, v149, vcc
	s_waitcnt lgkmcnt(0)
	v_mov_b32_e32 v50, v212
	v_mov_b32_e32 v51, v213
	v_mov_b32_e32 v52, v214
	v_mov_b32_e32 v53, v215
	v_mov_b32_e32 v54, v216
	v_mov_b32_e32 v55, v217
	v_mov_b32_e32 v56, v218
	v_mov_b32_e32 v57, v219
	v_lshlrev_b32_e32 v62, 16, v50
	v_and_b32_e32 v63, 0xffff0000, v50
	v_lshlrev_b32_e32 v50, 16, v51
	v_and_b32_e32 v51, 0xffff0000, v51
	v_lshlrev_b32_e32 v66, 16, v54
	v_and_b32_e32 v67, 0xffff0000, v54
	v_lshlrev_b32_e32 v54, 16, v55
	v_and_b32_e32 v55, 0xffff0000, v55
	v_lshlrev_b32_e32 v64, 16, v52
	v_and_b32_e32 v65, 0xffff0000, v52
	v_lshlrev_b32_e32 v52, 16, v53
	v_and_b32_e32 v53, 0xffff0000, v53
	v_lshlrev_b32_e32 v68, 16, v56
	v_and_b32_e32 v69, 0xffff0000, v56
	v_lshlrev_b32_e32 v56, 16, v57
	v_and_b32_e32 v57, 0xffff0000, v57
	v_pk_add_f32 v[48:49], v[48:49], v[50:51]
	v_pk_add_f32 v[46:47], v[46:47], v[62:63]
	v_pk_add_f32 v[40:41], v[40:41], v[54:55]
	v_pk_add_f32 v[38:39], v[38:39], v[66:67]
	v_pk_add_f32 v[44:45], v[44:45], v[52:53]
	v_pk_add_f32 v[42:43], v[42:43], v[64:65]
	v_pk_add_f32 v[50:51], v[36:37], v[56:57]
	v_pk_add_f32 v[52:53], v[34:35], v[68:69]
	v_mul_f32_e32 v36, v47, v47
	v_mul_f32_e32 v37, v49, v49
	v_mul_f32_e32 v56, v39, v39
	v_mul_f32_e32 v57, v41, v41
	v_cvt_pk_bf16_f32 v34, v46, v47
	v_mul_f32_e32 v47, v43, v43
	v_mul_f32_e32 v55, v53, v53
	v_fmac_f32_e32 v36, v46, v46
	v_fmac_f32_e32 v37, v48, v48
	v_fmac_f32_e32 v56, v38, v38
	v_fmac_f32_e32 v57, v40, v40
	v_cvt_pk_bf16_f32 v35, v48, v49
	v_mul_f32_e32 v49, v45, v45
	v_mul_f32_e32 v54, v51, v51
	v_fmac_f32_e32 v47, v42, v42
	v_fmac_f32_e32 v55, v52, v52
	v_add_f32_e32 v36, v36, v37
	v_add_f32_e32 v37, v56, v57
	v_fmac_f32_e32 v49, v44, v44
	v_fmac_f32_e32 v54, v50, v50
	v_add_f32_e32 v36, v47, v36
	v_add_f32_e32 v37, v55, v37
	v_add_f32_e32 v36, v49, v36
	v_add_f32_e32 v37, v54, v37
	v_add_f32_e32 v46, v36, v37
	ds_bpermute_b32 v47, v158, v46
	v_cvt_pk_bf16_f32 v36, v42, v43
	v_cvt_pk_bf16_f32 v37, v44, v45
	global_store_dwordx4 v[58:59], v[34:37], off
	s_waitcnt lgkmcnt(0)
	s_nop 0
	v_add_f32_e32 v34, v46, v47
	ds_bpermute_b32 v35, v114, v34
	v_cvt_pk_bf16_f32 v36, v38, v39
	v_cvt_pk_bf16_f32 v37, v40, v41
	v_cvt_pk_bf16_f32 v38, v52, v53
	v_cvt_pk_bf16_f32 v39, v50, v51
	global_store_dwordx4 v[60:61], v[36:39], off offset:256
	s_and_saveexec_b64 s[12:13], s[2:3]
	s_cbranch_execz .LBB0_382
	v_lshl_add_u64 v[36:37], v[146:147], 2, s[72:73]
	s_waitcnt lgkmcnt(0)
	v_add_f32_e32 v34, v34, v35
	global_atomic_add_f32 v[36:37], v34, off offset:576
.LBB0_382:
	s_or_b64 exec, exec, s[12:13]
	v_add_co_u32_e32 v42, vcc, 0x50000, v148
	v_lshl_add_u64 v[44:45], v[148:149], 0, s[18:19]
	s_nop 0
	v_addc_co_u32_e32 v43, vcc, 0, v149, vcc
	s_waitcnt lgkmcnt(0)
	v_mov_b32_e32 v34, v228
	v_mov_b32_e32 v35, v229
	v_mov_b32_e32 v36, v230
	v_mov_b32_e32 v37, v231
	v_mov_b32_e32 v38, v232
	v_mov_b32_e32 v39, v233
	v_mov_b32_e32 v40, v234
	v_mov_b32_e32 v41, v235
	v_lshlrev_b32_e32 v46, 16, v34
	v_and_b32_e32 v47, 0xffff0000, v34
	v_lshlrev_b32_e32 v34, 16, v35
	v_and_b32_e32 v35, 0xffff0000, v35
	v_lshlrev_b32_e32 v50, 16, v38
	v_and_b32_e32 v51, 0xffff0000, v38
	v_lshlrev_b32_e32 v38, 16, v39
	v_and_b32_e32 v39, 0xffff0000, v39
	v_lshlrev_b32_e32 v48, 16, v36
	v_and_b32_e32 v49, 0xffff0000, v36
	v_lshlrev_b32_e32 v36, 16, v37
	v_and_b32_e32 v37, 0xffff0000, v37
	v_lshlrev_b32_e32 v52, 16, v40
	v_and_b32_e32 v53, 0xffff0000, v40
	v_lshlrev_b32_e32 v40, 16, v41
	v_and_b32_e32 v41, 0xffff0000, v41
	v_pk_add_f32 v[32:33], v[32:33], v[34:35]
	v_pk_add_f32 v[30:31], v[30:31], v[46:47]
	v_pk_add_f32 v[24:25], v[24:25], v[38:39]
	v_pk_add_f32 v[22:23], v[22:23], v[50:51]
	v_pk_add_f32 v[28:29], v[28:29], v[36:37]
	v_pk_add_f32 v[26:27], v[26:27], v[48:49]
	v_pk_add_f32 v[34:35], v[20:21], v[40:41]
	v_pk_add_f32 v[36:37], v[18:19], v[52:53]
	v_mul_f32_e32 v20, v31, v31
	v_mul_f32_e32 v21, v33, v33
	v_mul_f32_e32 v40, v23, v23
	v_mul_f32_e32 v41, v25, v25
	v_cvt_pk_bf16_f32 v18, v30, v31
	v_mul_f32_e32 v31, v27, v27
	v_mul_f32_e32 v39, v37, v37
	v_fmac_f32_e32 v20, v30, v30
	v_fmac_f32_e32 v21, v32, v32
	v_fmac_f32_e32 v40, v22, v22
	v_fmac_f32_e32 v41, v24, v24
	v_cvt_pk_bf16_f32 v19, v32, v33
	v_mul_f32_e32 v33, v29, v29
	v_mul_f32_e32 v38, v35, v35
	v_fmac_f32_e32 v31, v26, v26
	v_fmac_f32_e32 v39, v36, v36
	v_add_f32_e32 v20, v20, v21
	v_add_f32_e32 v21, v40, v41
	v_fmac_f32_e32 v33, v28, v28
	v_fmac_f32_e32 v38, v34, v34
	v_add_f32_e32 v20, v31, v20
	v_add_f32_e32 v21, v39, v21
	v_add_f32_e32 v20, v33, v20
	v_add_f32_e32 v21, v38, v21
	v_add_f32_e32 v30, v20, v21
	ds_bpermute_b32 v31, v158, v30
	v_cvt_pk_bf16_f32 v20, v26, v27
	v_cvt_pk_bf16_f32 v21, v28, v29
	global_store_dwordx4 v[42:43], v[18:21], off
	s_waitcnt lgkmcnt(0)
	s_nop 0
	v_add_f32_e32 v18, v30, v31
	ds_bpermute_b32 v19, v114, v18
	v_cvt_pk_bf16_f32 v20, v22, v23
	v_cvt_pk_bf16_f32 v21, v24, v25
	v_cvt_pk_bf16_f32 v22, v36, v37
	v_cvt_pk_bf16_f32 v23, v34, v35
	global_store_dwordx4 v[44:45], v[20:23], off offset:256
	s_and_saveexec_b64 s[12:13], s[2:3]
	s_cbranch_execz .LBB0_384
	v_lshl_add_u64 v[20:21], v[146:147], 2, s[72:73]
	s_waitcnt lgkmcnt(0)
	v_add_f32_e32 v18, v18, v19
	global_atomic_add_f32 v[20:21], v18, off offset:640
.LBB0_384:
	s_or_b64 exec, exec, s[12:13]
	v_add_co_u32_e32 v26, vcc, 0x58000, v148
	v_lshl_add_u64 v[28:29], v[148:149], 0, s[20:21]
	s_nop 0
	v_addc_co_u32_e32 v27, vcc, 0, v149, vcc
	s_waitcnt lgkmcnt(0)
	v_mov_b32_e32 v18, v236
	v_mov_b32_e32 v19, v237
	v_mov_b32_e32 v20, v238
	v_mov_b32_e32 v21, v239
	v_mov_b32_e32 v22, v240
	v_mov_b32_e32 v23, v241
	v_mov_b32_e32 v24, v242
	v_mov_b32_e32 v25, v243
	v_lshlrev_b32_e32 v30, 16, v18
	v_and_b32_e32 v31, 0xffff0000, v18
	v_lshlrev_b32_e32 v18, 16, v19
	v_and_b32_e32 v19, 0xffff0000, v19
	v_lshlrev_b32_e32 v34, 16, v22
	v_and_b32_e32 v35, 0xffff0000, v22
	v_lshlrev_b32_e32 v22, 16, v23
	v_and_b32_e32 v23, 0xffff0000, v23
	v_lshlrev_b32_e32 v32, 16, v20
	v_and_b32_e32 v33, 0xffff0000, v20
	v_lshlrev_b32_e32 v20, 16, v21
	v_and_b32_e32 v21, 0xffff0000, v21
	v_lshlrev_b32_e32 v36, 16, v24
	v_and_b32_e32 v37, 0xffff0000, v24
	v_lshlrev_b32_e32 v24, 16, v25
	v_and_b32_e32 v25, 0xffff0000, v25
	v_pk_add_f32 v[16:17], v[16:17], v[18:19]
	v_pk_add_f32 v[14:15], v[14:15], v[30:31]
	v_pk_add_f32 v[8:9], v[8:9], v[22:23]
	v_pk_add_f32 v[6:7], v[6:7], v[34:35]
	v_pk_add_f32 v[12:13], v[12:13], v[20:21]
	v_pk_add_f32 v[10:11], v[10:11], v[32:33]
	v_pk_add_f32 v[18:19], v[4:5], v[24:25]
	v_pk_add_f32 v[20:21], v[2:3], v[36:37]
	v_mul_f32_e32 v4, v15, v15
	v_mul_f32_e32 v5, v17, v17
	v_mul_f32_e32 v24, v7, v7
	v_mul_f32_e32 v25, v9, v9
	v_cvt_pk_bf16_f32 v2, v14, v15
	v_mul_f32_e32 v15, v11, v11
	v_mul_f32_e32 v23, v21, v21
	v_fmac_f32_e32 v4, v14, v14
	v_fmac_f32_e32 v5, v16, v16
	v_fmac_f32_e32 v24, v6, v6
	v_fmac_f32_e32 v25, v8, v8
	v_cvt_pk_bf16_f32 v3, v16, v17
	v_mul_f32_e32 v17, v13, v13
	v_mul_f32_e32 v22, v19, v19
	v_fmac_f32_e32 v15, v10, v10
	v_fmac_f32_e32 v23, v20, v20
	v_add_f32_e32 v4, v4, v5
	v_add_f32_e32 v5, v24, v25
	v_fmac_f32_e32 v17, v12, v12
	v_fmac_f32_e32 v22, v18, v18
	v_add_f32_e32 v4, v15, v4
	v_add_f32_e32 v5, v23, v5
	v_add_f32_e32 v4, v17, v4
	v_add_f32_e32 v5, v22, v5
	v_add_f32_e32 v14, v4, v5
	ds_bpermute_b32 v15, v158, v14
	v_cvt_pk_bf16_f32 v4, v10, v11
	v_cvt_pk_bf16_f32 v5, v12, v13
	global_store_dwordx4 v[26:27], v[2:5], off
	s_waitcnt lgkmcnt(0)
	s_nop 0
	v_add_f32_e32 v2, v14, v15
	ds_bpermute_b32 v3, v114, v2
	v_cvt_pk_bf16_f32 v4, v6, v7
	v_cvt_pk_bf16_f32 v5, v8, v9
	v_cvt_pk_bf16_f32 v6, v20, v21
	v_cvt_pk_bf16_f32 v7, v18, v19
	global_store_dwordx4 v[28:29], v[4:7], off offset:256
	s_and_saveexec_b64 s[12:13], s[2:3]
	s_cbranch_execz .LBB0_386
	v_lshl_add_u64 v[4:5], v[146:147], 2, s[72:73]
	s_waitcnt lgkmcnt(0)
	v_add_f32_e32 v2, v2, v3
	global_atomic_add_f32 v[4:5], v2, off offset:704

.LBB0_546:
	v_lshl_add_u32 v148, s24, 8, v1
	v_ashrrev_i32_e32 v149, 31, v148
	v_lshl_or_b32 v146, s26, 8, v151
	v_lshlrev_b64 v[156:157], 11, v[148:149]
	v_ashrrev_i32_e32 v147, 31, v146
	v_lshl_add_u64 v[156:157], s[78:79], 0, v[156:157]
	v_lshl_add_u64 v[166:167], v[146:147], 1, v[156:157]
	global_load_dwordx4 v[158:161], v[166:167], off
	global_load_dwordx4 v[162:165], v[166:167], off offset:256
	s_mov_b32 s95, 0
	s_mov_b32 s94, 0x8000
	v_lshl_add_u64 v[244:245], v[166:167], 0, s[94:95]
	global_load_dwordx4 v[176:179], v[244:245], off
	global_load_dwordx4 v[180:183], v[244:245], off offset:256
	s_mov_b32 s94, 0x10000
	v_lshl_add_u64 v[246:247], v[166:167], 0, s[94:95]
	global_load_dwordx4 v[184:187], v[246:247], off
	global_load_dwordx4 v[188:191], v[246:247], off offset:256
	s_mov_b32 s94, 0x18000
	v_lshl_add_u64 v[244:245], v[166:167], 0, s[94:95]
	global_load_dwordx4 v[192:195], v[244:245], off
	global_load_dwordx4 v[200:203], v[244:245], off offset:256
	s_mov_b32 s94, 0x40000
	v_lshl_add_u64 v[246:247], v[166:167], 0, s[94:95]
	global_load_dwordx4 v[204:207], v[246:247], off
	global_load_dwordx4 v[208:211], v[246:247], off offset:256
	s_mov_b32 s94, 0x48000
	v_lshl_add_u64 v[244:245], v[166:167], 0, s[94:95]
	global_load_dwordx4 v[212:215], v[244:245], off
	global_load_dwordx4 v[216:219], v[244:245], off offset:256
	s_mov_b32 s94, 0x50000
	v_lshl_add_u64 v[246:247], v[166:167], 0, s[94:95]
	global_load_dwordx4 v[228:231], v[246:247], off
	global_load_dwordx4 v[232:235], v[246:247], off offset:256
	s_mov_b32 s94, 0x58000
	v_lshl_add_u64 v[244:245], v[166:167], 0, s[94:95]
	global_load_dwordx4 v[236:239], v[244:245], off
	global_load_dwordx4 v[240:243], v[244:245], off offset:256
	v_and_b32_e32 v157, 64, v155
	v_xor_b32_e32 v156, 16, v155
	v_add_u32_e32 v157, 64, v157
	v_xor_b32_e32 v168, 32, v155
	v_cmp_lt_i32_e32 vcc, v156, v157
	s_waitcnt vmcnt(0)
	v_and_b32_e32 v169, 0xffff0000, v158
	v_cndmask_b32_e32 v156, v155, v156, vcc
	v_cmp_lt_i32_e32 vcc, v168, v157
	v_lshlrev_b32_e32 v172, 16, v162
	v_and_b32_e32 v173, 0xffff0000, v162
	v_cndmask_b32_e32 v157, v155, v168, vcc
	v_lshlrev_b32_e32 v168, 16, v158
	v_lshlrev_b32_e32 v158, 16, v159
	v_and_b32_e32 v159, 0xffff0000, v159
	v_lshlrev_b32_e32 v162, 16, v163
	v_and_b32_e32 v163, 0xffff0000, v163
	v_lshlrev_b32_e32 v170, 16, v160
	v_and_b32_e32 v171, 0xffff0000, v160
	v_lshlrev_b32_e32 v160, 16, v161
	v_and_b32_e32 v161, 0xffff0000, v161
	v_lshlrev_b32_e32 v174, 16, v164
	v_and_b32_e32 v175, 0xffff0000, v164
	v_lshlrev_b32_e32 v164, 16, v165
	v_and_b32_e32 v165, 0xffff0000, v165
	v_pk_add_f32 v[128:129], v[128:129], v[158:159]
	v_pk_add_f32 v[126:127], v[126:127], v[168:169]
	v_pk_add_f32 v[120:121], v[120:121], v[162:163]
	v_pk_add_f32 v[118:119], v[118:119], v[172:173]
	v_pk_add_f32 v[124:125], v[124:125], v[160:161]
	v_pk_add_f32 v[122:123], v[122:123], v[170:171]
	v_pk_add_f32 v[158:159], v[116:117], v[164:165]
	v_pk_add_f32 v[160:161], v[114:115], v[174:175]
	v_mul_f32_e32 v116, v127, v127
	v_mul_f32_e32 v117, v129, v129
	v_mul_f32_e32 v164, v119, v119
	v_mul_f32_e32 v165, v121, v121
	v_cvt_pk_bf16_f32 v114, v126, v127
	v_mul_f32_e32 v127, v123, v123
	v_mul_f32_e32 v163, v161, v161
	v_fmac_f32_e32 v116, v126, v126
	v_fmac_f32_e32 v117, v128, v128
	v_fmac_f32_e32 v164, v118, v118
	v_fmac_f32_e32 v165, v120, v120
	v_cvt_pk_bf16_f32 v115, v128, v129
	v_mul_f32_e32 v129, v125, v125
	v_mul_f32_e32 v162, v159, v159
	v_fmac_f32_e32 v127, v122, v122
	v_fmac_f32_e32 v163, v160, v160
	v_add_f32_e32 v116, v116, v117
	v_add_f32_e32 v117, v164, v165
	v_fmac_f32_e32 v129, v124, v124
	v_fmac_f32_e32 v162, v158, v158
	v_add_f32_e32 v116, v127, v116
	v_add_f32_e32 v117, v163, v117
	v_add_f32_e32 v116, v129, v116
	v_add_f32_e32 v117, v162, v117
	v_lshlrev_b32_e32 v156, 2, v156
	v_add_f32_e32 v126, v116, v117
	ds_bpermute_b32 v127, v156, v126
	v_cvt_pk_bf16_f32 v116, v122, v123
	v_cvt_pk_bf16_f32 v117, v124, v125
	global_store_dwordx4 v[166:167], v[114:117], off
	v_cvt_pk_bf16_f32 v118, v118, v119
	v_cvt_pk_bf16_f32 v119, v120, v121
	s_waitcnt lgkmcnt(0)
	v_add_f32_e32 v114, v126, v127
	v_lshlrev_b32_e32 v116, 2, v157
	ds_bpermute_b32 v115, v116, v114
	v_cvt_pk_bf16_f32 v120, v160, v161
	v_cvt_pk_bf16_f32 v121, v158, v159
	global_store_dwordx4 v[166:167], v[118:121], off offset:256
	s_and_saveexec_b64 s[12:13], s[2:3]
	s_cbranch_execz .LBB0_548
	v_lshl_add_u64 v[118:119], v[148:149], 2, s[0:1]
	s_waitcnt lgkmcnt(0)
	v_add_f32_e32 v114, v114, v115
	global_atomic_add_f32 v[118:119], v114, off
.LBB0_548:
	s_or_b64 exec, exec, s[12:13]
	v_or_b32_e32 v114, 16, v148
	s_waitcnt lgkmcnt(0)
	v_ashrrev_i32_e32 v115, 31, v114
	v_lshlrev_b64 v[118:119], 11, v[114:115]
	v_lshl_add_u64 v[118:119], s[78:79], 0, v[118:119]
	v_lshl_add_u64 v[126:127], v[146:147], 1, v[118:119]
	v_mov_b32_e32 v118, v176
	v_mov_b32_e32 v119, v177
	v_mov_b32_e32 v120, v178
	v_mov_b32_e32 v121, v179
	v_mov_b32_e32 v122, v180
	v_mov_b32_e32 v123, v181
	v_mov_b32_e32 v124, v182
	v_mov_b32_e32 v125, v183
	v_lshlrev_b32_e32 v128, 16, v118
	v_and_b32_e32 v129, 0xffff0000, v118
	v_lshlrev_b32_e32 v118, 16, v119
	v_and_b32_e32 v119, 0xffff0000, v119
	v_lshlrev_b32_e32 v160, 16, v122
	v_and_b32_e32 v161, 0xffff0000, v122
	v_lshlrev_b32_e32 v122, 16, v123
	v_and_b32_e32 v123, 0xffff0000, v123
	v_lshlrev_b32_e32 v158, 16, v120
	v_and_b32_e32 v159, 0xffff0000, v120
	v_lshlrev_b32_e32 v120, 16, v121
	v_and_b32_e32 v121, 0xffff0000, v121
	v_lshlrev_b32_e32 v162, 16, v124
	v_and_b32_e32 v163, 0xffff0000, v124
	v_lshlrev_b32_e32 v124, 16, v125
	v_and_b32_e32 v125, 0xffff0000, v125
	v_pk_add_f32 v[112:113], v[112:113], v[118:119]
	v_pk_add_f32 v[110:111], v[110:111], v[128:129]
	v_pk_add_f32 v[104:105], v[104:105], v[122:123]
	v_pk_add_f32 v[102:103], v[102:103], v[160:161]
	v_pk_add_f32 v[108:109], v[108:109], v[120:121]
	v_pk_add_f32 v[106:107], v[106:107], v[158:159]
	v_pk_add_f32 v[118:119], v[100:101], v[124:125]
	v_pk_add_f32 v[120:121], v[98:99], v[162:163]
	v_mul_f32_e32 v100, v111, v111
	v_mul_f32_e32 v101, v113, v113
	v_mul_f32_e32 v123, v103, v103
	v_mul_f32_e32 v124, v105, v105
	v_cvt_pk_bf16_f32 v98, v110, v111
	v_mul_f32_e32 v111, v107, v107
	v_mul_f32_e32 v122, v121, v121
	v_fmac_f32_e32 v100, v110, v110
	v_fmac_f32_e32 v101, v112, v112
	v_fmac_f32_e32 v123, v102, v102
	v_fmac_f32_e32 v124, v104, v104
	v_cvt_pk_bf16_f32 v99, v112, v113
	v_mul_f32_e32 v113, v109, v109
	v_mul_f32_e32 v117, v119, v119
	v_fmac_f32_e32 v111, v106, v106
	v_fmac_f32_e32 v122, v120, v120
	v_add_f32_e32 v100, v100, v101
	v_add_f32_e32 v101, v123, v124
	v_fmac_f32_e32 v113, v108, v108
	v_fmac_f32_e32 v117, v118, v118
	v_add_f32_e32 v100, v111, v100
	v_add_f32_e32 v101, v122, v101
	v_add_f32_e32 v100, v113, v100
	v_add_f32_e32 v101, v117, v101
	v_add_f32_e32 v110, v100, v101
	ds_bpermute_b32 v111, v156, v110
	v_cvt_pk_bf16_f32 v100, v106, v107
	v_cvt_pk_bf16_f32 v101, v108, v109
	global_store_dwordx4 v[126:127], v[98:101], off
	s_waitcnt lgkmcnt(0)
	s_nop 0
	v_add_f32_e32 v98, v110, v111
	ds_bpermute_b32 v99, v116, v98
	v_cvt_pk_bf16_f32 v100, v102, v103
	v_cvt_pk_bf16_f32 v101, v104, v105
	v_cvt_pk_bf16_f32 v102, v120, v121
	v_cvt_pk_bf16_f32 v103, v118, v119
	global_store_dwordx4 v[126:127], v[100:103], off offset:256
	s_and_saveexec_b64 s[12:13], s[2:3]
	s_cbranch_execz .LBB0_550
	v_lshl_add_u64 v[100:101], v[114:115], 2, s[0:1]
	s_waitcnt lgkmcnt(0)
	v_add_f32_e32 v98, v98, v99
	global_atomic_add_f32 v[100:101], v98, off
.LBB0_550:
	s_or_b64 exec, exec, s[12:13]
	v_or_b32_e32 v98, 32, v148
	s_waitcnt lgkmcnt(0)
	v_ashrrev_i32_e32 v99, 31, v98
	v_lshlrev_b64 v[100:101], 11, v[98:99]
	v_lshl_add_u64 v[100:101], s[78:79], 0, v[100:101]
	v_lshl_add_u64 v[108:109], v[146:147], 1, v[100:101]
	v_mov_b32_e32 v100, v184
	v_mov_b32_e32 v101, v185
	v_mov_b32_e32 v102, v186
	v_mov_b32_e32 v103, v187
	v_mov_b32_e32 v104, v188
	v_mov_b32_e32 v105, v189
	v_mov_b32_e32 v106, v190
	v_mov_b32_e32 v107, v191
	v_lshlrev_b32_e32 v110, 16, v100
	v_and_b32_e32 v111, 0xffff0000, v100
	v_lshlrev_b32_e32 v100, 16, v101
	v_and_b32_e32 v101, 0xffff0000, v101
	v_lshlrev_b32_e32 v114, 16, v104
	v_and_b32_e32 v115, 0xffff0000, v104
	v_lshlrev_b32_e32 v104, 16, v105
	v_and_b32_e32 v105, 0xffff0000, v105
	v_lshlrev_b32_e32 v112, 16, v102
	v_and_b32_e32 v113, 0xffff0000, v102
	v_lshlrev_b32_e32 v102, 16, v103
	v_and_b32_e32 v103, 0xffff0000, v103
	v_lshlrev_b32_e32 v118, 16, v106
	v_and_b32_e32 v119, 0xffff0000, v106
	v_lshlrev_b32_e32 v106, 16, v107
	v_and_b32_e32 v107, 0xffff0000, v107
	v_pk_add_f32 v[96:97], v[96:97], v[100:101]
	v_pk_add_f32 v[94:95], v[94:95], v[110:111]
	v_pk_add_f32 v[88:89], v[88:89], v[104:105]
	v_pk_add_f32 v[86:87], v[86:87], v[114:115]
	v_pk_add_f32 v[92:93], v[92:93], v[102:103]
	v_pk_add_f32 v[90:91], v[90:91], v[112:113]
	v_pk_add_f32 v[100:101], v[84:85], v[106:107]
	v_pk_add_f32 v[102:103], v[82:83], v[118:119]
	v_mul_f32_e32 v84, v95, v95
	v_mul_f32_e32 v85, v97, v97
	v_mul_f32_e32 v106, v87, v87
	v_mul_f32_e32 v107, v89, v89
	v_cvt_pk_bf16_f32 v82, v94, v95
	v_mul_f32_e32 v95, v91, v91
	v_mul_f32_e32 v105, v103, v103
	v_fmac_f32_e32 v84, v94, v94
	v_fmac_f32_e32 v85, v96, v96
	v_fmac_f32_e32 v106, v86, v86
	v_fmac_f32_e32 v107, v88, v88
	v_cvt_pk_bf16_f32 v83, v96, v97
	v_mul_f32_e32 v97, v93, v93
	v_mul_f32_e32 v104, v101, v101
	v_fmac_f32_e32 v95, v90, v90
	v_fmac_f32_e32 v105, v102, v102
	v_add_f32_e32 v84, v84, v85
	v_add_f32_e32 v85, v106, v107
	v_fmac_f32_e32 v97, v92, v92
	v_fmac_f32_e32 v104, v100, v100
	v_add_f32_e32 v84, v95, v84
	v_add_f32_e32 v85, v105, v85
	v_add_f32_e32 v84, v97, v84
	v_add_f32_e32 v85, v104, v85
	v_add_f32_e32 v94, v84, v85
	ds_bpermute_b32 v95, v156, v94
	v_cvt_pk_bf16_f32 v84, v90, v91
	v_cvt_pk_bf16_f32 v85, v92, v93
	global_store_dwordx4 v[108:109], v[82:85], off
	s_waitcnt lgkmcnt(0)
	s_nop 0
	v_add_f32_e32 v82, v94, v95
	ds_bpermute_b32 v83, v116, v82
	v_cvt_pk_bf16_f32 v84, v86, v87
	v_cvt_pk_bf16_f32 v85, v88, v89
	v_cvt_pk_bf16_f32 v86, v102, v103
	v_cvt_pk_bf16_f32 v87, v100, v101
	global_store_dwordx4 v[108:109], v[84:87], off offset:256
	s_and_saveexec_b64 s[12:13], s[2:3]
	s_cbranch_execz .LBB0_552
	v_lshl_add_u64 v[84:85], v[98:99], 2, s[0:1]
	s_waitcnt lgkmcnt(0)
	v_add_f32_e32 v82, v82, v83
	global_atomic_add_f32 v[84:85], v82, off
.LBB0_552:
	s_or_b64 exec, exec, s[12:13]
	v_or_b32_e32 v82, 48, v148
	s_waitcnt lgkmcnt(0)
	v_ashrrev_i32_e32 v83, 31, v82
	v_lshlrev_b64 v[84:85], 11, v[82:83]
	v_lshl_add_u64 v[84:85], s[78:79], 0, v[84:85]
	v_lshl_add_u64 v[92:93], v[146:147], 1, v[84:85]
	v_mov_b32_e32 v84, v192
	v_mov_b32_e32 v85, v193
	v_mov_b32_e32 v86, v194
	v_mov_b32_e32 v87, v195
	v_mov_b32_e32 v88, v200
	v_mov_b32_e32 v89, v201
	v_mov_b32_e32 v90, v202
	v_mov_b32_e32 v91, v203
	v_lshlrev_b32_e32 v94, 16, v84
	v_and_b32_e32 v95, 0xffff0000, v84
	v_lshlrev_b32_e32 v84, 16, v85
	v_and_b32_e32 v85, 0xffff0000, v85
	v_lshlrev_b32_e32 v98, 16, v88
	v_and_b32_e32 v99, 0xffff0000, v88
	v_lshlrev_b32_e32 v88, 16, v89
	v_and_b32_e32 v89, 0xffff0000, v89
	v_lshlrev_b32_e32 v96, 16, v86
	v_and_b32_e32 v97, 0xffff0000, v86
	v_lshlrev_b32_e32 v86, 16, v87
	v_and_b32_e32 v87, 0xffff0000, v87
	v_lshlrev_b32_e32 v100, 16, v90
	v_and_b32_e32 v101, 0xffff0000, v90
	v_lshlrev_b32_e32 v90, 16, v91
	v_and_b32_e32 v91, 0xffff0000, v91
	v_pk_add_f32 v[80:81], v[80:81], v[84:85]
	v_pk_add_f32 v[78:79], v[78:79], v[94:95]
	v_pk_add_f32 v[72:73], v[72:73], v[88:89]
	v_pk_add_f32 v[70:71], v[70:71], v[98:99]
	v_pk_add_f32 v[76:77], v[76:77], v[86:87]
	v_pk_add_f32 v[74:75], v[74:75], v[96:97]
	v_pk_add_f32 v[84:85], v[68:69], v[90:91]
	v_pk_add_f32 v[86:87], v[66:67], v[100:101]
	v_mul_f32_e32 v68, v79, v79
	v_mul_f32_e32 v69, v81, v81
	v_mul_f32_e32 v90, v71, v71
	v_mul_f32_e32 v91, v73, v73
	v_cvt_pk_bf16_f32 v66, v78, v79
	v_mul_f32_e32 v79, v75, v75
	v_mul_f32_e32 v89, v87, v87
	v_fmac_f32_e32 v68, v78, v78
	v_fmac_f32_e32 v69, v80, v80
	v_fmac_f32_e32 v90, v70, v70
	v_fmac_f32_e32 v91, v72, v72
	v_cvt_pk_bf16_f32 v67, v80, v81
	v_mul_f32_e32 v81, v77, v77
	v_mul_f32_e32 v88, v85, v85
	v_fmac_f32_e32 v79, v74, v74
	v_fmac_f32_e32 v89, v86, v86
	v_add_f32_e32 v68, v68, v69
	v_add_f32_e32 v69, v90, v91
	v_fmac_f32_e32 v81, v76, v76
	v_fmac_f32_e32 v88, v84, v84
	v_add_f32_e32 v68, v79, v68
	v_add_f32_e32 v69, v89, v69
	v_add_f32_e32 v68, v81, v68
	v_add_f32_e32 v69, v88, v69
	v_add_f32_e32 v78, v68, v69
	ds_bpermute_b32 v79, v156, v78
	v_cvt_pk_bf16_f32 v68, v74, v75
	v_cvt_pk_bf16_f32 v69, v76, v77
	global_store_dwordx4 v[92:93], v[66:69], off
	s_waitcnt lgkmcnt(0)
	s_nop 0
	v_add_f32_e32 v66, v78, v79
	ds_bpermute_b32 v67, v116, v66
	v_cvt_pk_bf16_f32 v68, v70, v71
	v_cvt_pk_bf16_f32 v69, v72, v73
	v_cvt_pk_bf16_f32 v70, v86, v87
	v_cvt_pk_bf16_f32 v71, v84, v85
	global_store_dwordx4 v[92:93], v[68:71], off offset:256
	s_and_saveexec_b64 s[12:13], s[2:3]
	s_cbranch_execz .LBB0_554
	v_lshl_add_u64 v[68:69], v[82:83], 2, s[0:1]
	s_waitcnt lgkmcnt(0)
	v_add_f32_e32 v66, v66, v67
	global_atomic_add_f32 v[68:69], v66, off
.LBB0_554:
	s_or_b64 exec, exec, s[12:13]
	v_add_u32_e32 v66, 0x80, v148
	s_waitcnt lgkmcnt(0)
	v_ashrrev_i32_e32 v67, 31, v66
	v_lshlrev_b64 v[68:69], 11, v[66:67]
	v_lshl_add_u64 v[68:69], s[78:79], 0, v[68:69]
	v_lshl_add_u64 v[76:77], v[146:147], 1, v[68:69]
	v_mov_b32_e32 v68, v204
	v_mov_b32_e32 v69, v205
	v_mov_b32_e32 v70, v206
	v_mov_b32_e32 v71, v207
	v_mov_b32_e32 v72, v208
	v_mov_b32_e32 v73, v209
	v_mov_b32_e32 v74, v210
	v_mov_b32_e32 v75, v211
	v_lshlrev_b32_e32 v78, 16, v68
	v_and_b32_e32 v79, 0xffff0000, v68
	v_lshlrev_b32_e32 v68, 16, v69
	v_and_b32_e32 v69, 0xffff0000, v69
	v_lshlrev_b32_e32 v82, 16, v72
	v_and_b32_e32 v83, 0xffff0000, v72
	v_lshlrev_b32_e32 v72, 16, v73
	v_and_b32_e32 v73, 0xffff0000, v73
	v_lshlrev_b32_e32 v80, 16, v70
	v_and_b32_e32 v81, 0xffff0000, v70
	v_lshlrev_b32_e32 v70, 16, v71
	v_and_b32_e32 v71, 0xffff0000, v71
	v_lshlrev_b32_e32 v84, 16, v74
	v_and_b32_e32 v85, 0xffff0000, v74
	v_lshlrev_b32_e32 v74, 16, v75
	v_and_b32_e32 v75, 0xffff0000, v75
	v_pk_add_f32 v[64:65], v[64:65], v[68:69]
	v_pk_add_f32 v[62:63], v[62:63], v[78:79]
	v_pk_add_f32 v[56:57], v[56:57], v[72:73]
	v_pk_add_f32 v[54:55], v[54:55], v[82:83]
	v_pk_add_f32 v[60:61], v[60:61], v[70:71]
	v_pk_add_f32 v[58:59], v[58:59], v[80:81]
	v_pk_add_f32 v[68:69], v[52:53], v[74:75]
	v_pk_add_f32 v[70:71], v[50:51], v[84:85]
	v_mul_f32_e32 v52, v63, v63
	v_mul_f32_e32 v53, v65, v65
	v_mul_f32_e32 v74, v55, v55
	v_mul_f32_e32 v75, v57, v57
	v_cvt_pk_bf16_f32 v50, v62, v63
	v_mul_f32_e32 v63, v59, v59
	v_mul_f32_e32 v73, v71, v71
	v_fmac_f32_e32 v52, v62, v62
	v_fmac_f32_e32 v53, v64, v64
	v_fmac_f32_e32 v74, v54, v54
	v_fmac_f32_e32 v75, v56, v56
	v_cvt_pk_bf16_f32 v51, v64, v65
	v_mul_f32_e32 v65, v61, v61
	v_mul_f32_e32 v72, v69, v69
	v_fmac_f32_e32 v63, v58, v58
	v_fmac_f32_e32 v73, v70, v70
	v_add_f32_e32 v52, v52, v53
	v_add_f32_e32 v53, v74, v75
	v_fmac_f32_e32 v65, v60, v60
	v_fmac_f32_e32 v72, v68, v68
	v_add_f32_e32 v52, v63, v52
	v_add_f32_e32 v53, v73, v53
	v_add_f32_e32 v52, v65, v52
	v_add_f32_e32 v53, v72, v53
	v_add_f32_e32 v62, v52, v53
	ds_bpermute_b32 v63, v156, v62
	v_cvt_pk_bf16_f32 v52, v58, v59
	v_cvt_pk_bf16_f32 v53, v60, v61
	global_store_dwordx4 v[76:77], v[50:53], off
	s_waitcnt lgkmcnt(0)
	s_nop 0
	v_add_f32_e32 v50, v62, v63
	ds_bpermute_b32 v51, v116, v50
	v_cvt_pk_bf16_f32 v52, v54, v55
	v_cvt_pk_bf16_f32 v53, v56, v57
	v_cvt_pk_bf16_f32 v54, v70, v71
	v_cvt_pk_bf16_f32 v55, v68, v69
	global_store_dwordx4 v[76:77], v[52:55], off offset:256
	s_and_saveexec_b64 s[12:13], s[2:3]
	s_cbranch_execz .LBB0_556
	v_lshl_add_u64 v[52:53], v[66:67], 2, s[0:1]
	s_waitcnt lgkmcnt(0)
	v_add_f32_e32 v50, v50, v51
	global_atomic_add_f32 v[52:53], v50, off
.LBB0_556:
	s_or_b64 exec, exec, s[12:13]
	v_add_u32_e32 v50, 0x90, v148
	s_waitcnt lgkmcnt(0)
	v_ashrrev_i32_e32 v51, 31, v50
	v_lshlrev_b64 v[52:53], 11, v[50:51]
	v_lshl_add_u64 v[52:53], s[78:79], 0, v[52:53]
	v_lshl_add_u64 v[60:61], v[146:147], 1, v[52:53]
	v_mov_b32_e32 v52, v212
	v_mov_b32_e32 v53, v213
	v_mov_b32_e32 v54, v214
	v_mov_b32_e32 v55, v215
	v_mov_b32_e32 v56, v216
	v_mov_b32_e32 v57, v217
	v_mov_b32_e32 v58, v218
	v_mov_b32_e32 v59, v219
	v_lshlrev_b32_e32 v62, 16, v52
	v_and_b32_e32 v63, 0xffff0000, v52
	v_lshlrev_b32_e32 v52, 16, v53
	v_and_b32_e32 v53, 0xffff0000, v53
	v_lshlrev_b32_e32 v66, 16, v56
	v_and_b32_e32 v67, 0xffff0000, v56
	v_lshlrev_b32_e32 v56, 16, v57
	v_and_b32_e32 v57, 0xffff0000, v57
	v_lshlrev_b32_e32 v64, 16, v54
	v_and_b32_e32 v65, 0xffff0000, v54
	v_lshlrev_b32_e32 v54, 16, v55
	v_and_b32_e32 v55, 0xffff0000, v55
	v_lshlrev_b32_e32 v68, 16, v58
	v_and_b32_e32 v69, 0xffff0000, v58
	v_lshlrev_b32_e32 v58, 16, v59
	v_and_b32_e32 v59, 0xffff0000, v59
	v_pk_add_f32 v[48:49], v[48:49], v[52:53]
	v_pk_add_f32 v[46:47], v[46:47], v[62:63]
	v_pk_add_f32 v[40:41], v[40:41], v[56:57]
	v_pk_add_f32 v[38:39], v[38:39], v[66:67]
	v_pk_add_f32 v[44:45], v[44:45], v[54:55]
	v_pk_add_f32 v[42:43], v[42:43], v[64:65]
	v_pk_add_f32 v[52:53], v[36:37], v[58:59]
	v_pk_add_f32 v[54:55], v[34:35], v[68:69]
	v_mul_f32_e32 v36, v47, v47
	v_mul_f32_e32 v37, v49, v49
	v_mul_f32_e32 v58, v39, v39
	v_mul_f32_e32 v59, v41, v41
	v_cvt_pk_bf16_f32 v34, v46, v47
	v_mul_f32_e32 v47, v43, v43
	v_mul_f32_e32 v57, v55, v55
	v_fmac_f32_e32 v36, v46, v46
	v_fmac_f32_e32 v37, v48, v48
	v_fmac_f32_e32 v58, v38, v38
	v_fmac_f32_e32 v59, v40, v40
	v_cvt_pk_bf16_f32 v35, v48, v49
	v_mul_f32_e32 v49, v45, v45
	v_mul_f32_e32 v56, v53, v53
	v_fmac_f32_e32 v47, v42, v42
	v_fmac_f32_e32 v57, v54, v54
	v_add_f32_e32 v36, v36, v37
	v_add_f32_e32 v37, v58, v59
	v_fmac_f32_e32 v49, v44, v44
	v_fmac_f32_e32 v56, v52, v52
	v_add_f32_e32 v36, v47, v36
	v_add_f32_e32 v37, v57, v37
	v_add_f32_e32 v36, v49, v36
	v_add_f32_e32 v37, v56, v37
	v_add_f32_e32 v46, v36, v37
	ds_bpermute_b32 v47, v156, v46
	v_cvt_pk_bf16_f32 v36, v42, v43
	v_cvt_pk_bf16_f32 v37, v44, v45
	global_store_dwordx4 v[60:61], v[34:37], off
	s_waitcnt lgkmcnt(0)
	s_nop 0
	v_add_f32_e32 v34, v46, v47
	ds_bpermute_b32 v35, v116, v34
	v_cvt_pk_bf16_f32 v36, v38, v39
	v_cvt_pk_bf16_f32 v37, v40, v41
	v_cvt_pk_bf16_f32 v38, v54, v55
	v_cvt_pk_bf16_f32 v39, v52, v53
	global_store_dwordx4 v[60:61], v[36:39], off offset:256
	s_and_saveexec_b64 s[12:13], s[2:3]
	s_cbranch_execz .LBB0_558
	v_lshl_add_u64 v[36:37], v[50:51], 2, s[0:1]
	s_waitcnt lgkmcnt(0)
	v_add_f32_e32 v34, v34, v35
	global_atomic_add_f32 v[36:37], v34, off
.LBB0_558:
	s_or_b64 exec, exec, s[12:13]
	v_add_u32_e32 v34, 0xa0, v148
	s_waitcnt lgkmcnt(0)
	v_ashrrev_i32_e32 v35, 31, v34
	v_lshlrev_b64 v[36:37], 11, v[34:35]
	v_lshl_add_u64 v[36:37], s[78:79], 0, v[36:37]
	v_lshl_add_u64 v[44:45], v[146:147], 1, v[36:37]
	v_mov_b32_e32 v36, v228
	v_mov_b32_e32 v37, v229
	v_mov_b32_e32 v38, v230
	v_mov_b32_e32 v39, v231
	v_mov_b32_e32 v40, v232
	v_mov_b32_e32 v41, v233
	v_mov_b32_e32 v42, v234
	v_mov_b32_e32 v43, v235
	v_lshlrev_b32_e32 v46, 16, v36
	v_and_b32_e32 v47, 0xffff0000, v36
	v_lshlrev_b32_e32 v36, 16, v37
	v_and_b32_e32 v37, 0xffff0000, v37
	v_lshlrev_b32_e32 v50, 16, v40
	v_and_b32_e32 v51, 0xffff0000, v40
	v_lshlrev_b32_e32 v40, 16, v41
	v_and_b32_e32 v41, 0xffff0000, v41
	v_lshlrev_b32_e32 v48, 16, v38
	v_and_b32_e32 v49, 0xffff0000, v38
	v_lshlrev_b32_e32 v38, 16, v39
	v_and_b32_e32 v39, 0xffff0000, v39
	v_lshlrev_b32_e32 v52, 16, v42
	v_and_b32_e32 v53, 0xffff0000, v42
	v_lshlrev_b32_e32 v42, 16, v43
	v_and_b32_e32 v43, 0xffff0000, v43
	v_pk_add_f32 v[32:33], v[32:33], v[36:37]
	v_pk_add_f32 v[30:31], v[30:31], v[46:47]
	v_pk_add_f32 v[24:25], v[24:25], v[40:41]
	v_pk_add_f32 v[22:23], v[22:23], v[50:51]
	v_pk_add_f32 v[28:29], v[28:29], v[38:39]
	v_pk_add_f32 v[26:27], v[26:27], v[48:49]
	v_pk_add_f32 v[36:37], v[20:21], v[42:43]
	v_pk_add_f32 v[38:39], v[18:19], v[52:53]
	v_mul_f32_e32 v20, v31, v31
	v_mul_f32_e32 v21, v33, v33
	v_mul_f32_e32 v42, v23, v23
	v_mul_f32_e32 v43, v25, v25
	v_cvt_pk_bf16_f32 v18, v30, v31
	v_mul_f32_e32 v31, v27, v27
	v_mul_f32_e32 v41, v39, v39
	v_fmac_f32_e32 v20, v30, v30
	v_fmac_f32_e32 v21, v32, v32
	v_fmac_f32_e32 v42, v22, v22
	v_fmac_f32_e32 v43, v24, v24
	v_cvt_pk_bf16_f32 v19, v32, v33
	v_mul_f32_e32 v33, v29, v29
	v_mul_f32_e32 v40, v37, v37
	v_fmac_f32_e32 v31, v26, v26
	v_fmac_f32_e32 v41, v38, v38
	v_add_f32_e32 v20, v20, v21
	v_add_f32_e32 v21, v42, v43
	v_fmac_f32_e32 v33, v28, v28
	v_fmac_f32_e32 v40, v36, v36
	v_add_f32_e32 v20, v31, v20
	v_add_f32_e32 v21, v41, v21
	v_add_f32_e32 v20, v33, v20
	v_add_f32_e32 v21, v40, v21
	v_add_f32_e32 v30, v20, v21
	ds_bpermute_b32 v31, v156, v30
	v_cvt_pk_bf16_f32 v20, v26, v27
	v_cvt_pk_bf16_f32 v21, v28, v29
	global_store_dwordx4 v[44:45], v[18:21], off
	s_waitcnt lgkmcnt(0)
	s_nop 0
	v_add_f32_e32 v18, v30, v31
	ds_bpermute_b32 v19, v116, v18
	v_cvt_pk_bf16_f32 v20, v22, v23
	v_cvt_pk_bf16_f32 v21, v24, v25
	v_cvt_pk_bf16_f32 v22, v38, v39
	v_cvt_pk_bf16_f32 v23, v36, v37
	global_store_dwordx4 v[44:45], v[20:23], off offset:256
	s_and_saveexec_b64 s[12:13], s[2:3]
	s_cbranch_execz .LBB0_560
	v_lshl_add_u64 v[20:21], v[34:35], 2, s[0:1]
	s_waitcnt lgkmcnt(0)
	v_add_f32_e32 v18, v18, v19
	global_atomic_add_f32 v[20:21], v18, off
.LBB0_560:
	s_or_b64 exec, exec, s[12:13]
	v_add_u32_e32 v18, 0xb0, v148
	s_waitcnt lgkmcnt(0)
	v_ashrrev_i32_e32 v19, 31, v18
	v_lshlrev_b64 v[20:21], 11, v[18:19]
	v_lshl_add_u64 v[20:21], s[78:79], 0, v[20:21]
	v_lshl_add_u64 v[28:29], v[146:147], 1, v[20:21]
	v_mov_b32_e32 v20, v236
	v_mov_b32_e32 v21, v237
	v_mov_b32_e32 v22, v238
	v_mov_b32_e32 v23, v239
	v_mov_b32_e32 v24, v240
	v_mov_b32_e32 v25, v241
	v_mov_b32_e32 v26, v242
	v_mov_b32_e32 v27, v243
	v_lshlrev_b32_e32 v30, 16, v20
	v_and_b32_e32 v31, 0xffff0000, v20
	v_lshlrev_b32_e32 v20, 16, v21
	v_and_b32_e32 v21, 0xffff0000, v21
	v_lshlrev_b32_e32 v34, 16, v24
	v_and_b32_e32 v35, 0xffff0000, v24
	v_lshlrev_b32_e32 v24, 16, v25
	v_and_b32_e32 v25, 0xffff0000, v25
	v_lshlrev_b32_e32 v32, 16, v22
	v_and_b32_e32 v33, 0xffff0000, v22
	v_lshlrev_b32_e32 v22, 16, v23
	v_and_b32_e32 v23, 0xffff0000, v23
	v_lshlrev_b32_e32 v36, 16, v26
	v_and_b32_e32 v37, 0xffff0000, v26
	v_lshlrev_b32_e32 v26, 16, v27
	v_and_b32_e32 v27, 0xffff0000, v27
	v_pk_add_f32 v[16:17], v[16:17], v[20:21]
	v_pk_add_f32 v[14:15], v[14:15], v[30:31]
	v_pk_add_f32 v[8:9], v[8:9], v[24:25]
	v_pk_add_f32 v[6:7], v[6:7], v[34:35]
	v_pk_add_f32 v[12:13], v[12:13], v[22:23]
	v_pk_add_f32 v[10:11], v[10:11], v[32:33]
	v_pk_add_f32 v[20:21], v[4:5], v[26:27]
	v_pk_add_f32 v[22:23], v[2:3], v[36:37]
	v_mul_f32_e32 v4, v15, v15
	v_mul_f32_e32 v5, v17, v17
	v_mul_f32_e32 v26, v7, v7
	v_mul_f32_e32 v27, v9, v9
	v_cvt_pk_bf16_f32 v2, v14, v15
	v_mul_f32_e32 v15, v11, v11
	v_mul_f32_e32 v25, v23, v23
	v_fmac_f32_e32 v4, v14, v14
	v_fmac_f32_e32 v5, v16, v16
	v_fmac_f32_e32 v26, v6, v6
	v_fmac_f32_e32 v27, v8, v8
	v_cvt_pk_bf16_f32 v3, v16, v17
	v_mul_f32_e32 v17, v13, v13
	v_mul_f32_e32 v24, v21, v21
	v_fmac_f32_e32 v15, v10, v10
	v_fmac_f32_e32 v25, v22, v22
	v_add_f32_e32 v4, v4, v5
	v_add_f32_e32 v5, v26, v27
	v_fmac_f32_e32 v17, v12, v12
	v_fmac_f32_e32 v24, v20, v20
	v_add_f32_e32 v4, v15, v4
	v_add_f32_e32 v5, v25, v5
	v_add_f32_e32 v4, v17, v4
	v_add_f32_e32 v5, v24, v5
	v_add_f32_e32 v14, v4, v5
	ds_bpermute_b32 v15, v156, v14
	v_cvt_pk_bf16_f32 v4, v10, v11
	v_cvt_pk_bf16_f32 v5, v12, v13
	global_store_dwordx4 v[28:29], v[2:5], off
	s_waitcnt lgkmcnt(0)
	s_nop 0
	v_add_f32_e32 v2, v14, v15
	ds_bpermute_b32 v3, v116, v2
	v_cvt_pk_bf16_f32 v4, v6, v7
	v_cvt_pk_bf16_f32 v5, v8, v9
	v_cvt_pk_bf16_f32 v6, v22, v23
	v_cvt_pk_bf16_f32 v7, v20, v21
	global_store_dwordx4 v[28:29], v[4:7], off offset:256
	s_and_saveexec_b64 s[12:13], s[2:3]
	s_cbranch_execz .LBB0_562
	v_lshl_add_u64 v[4:5], v[18:19], 2, s[0:1]
	s_waitcnt lgkmcnt(0)
	v_add_f32_e32 v2, v2, v3
	global_atomic_add_f32 v[4:5], v2, off

.LBB0_1572:
	v_lshl_add_u32 v148, s24, 8, v1
	v_ashrrev_i32_e32 v149, 31, v148
	v_lshl_or_b32 v146, s26, 8, v151
	v_lshlrev_b64 v[156:157], 11, v[148:149]
	v_ashrrev_i32_e32 v147, 31, v146
	v_lshl_add_u64 v[156:157], s[78:79], 0, v[156:157]
	v_lshl_add_u64 v[166:167], v[146:147], 1, v[156:157]
	global_load_dwordx4 v[158:161], v[166:167], off
	global_load_dwordx4 v[162:165], v[166:167], off offset:256
	s_mov_b32 s95, 0
	s_mov_b32 s94, 0x8000
	v_lshl_add_u64 v[244:245], v[166:167], 0, s[94:95]
	global_load_dwordx4 v[176:179], v[244:245], off
	global_load_dwordx4 v[180:183], v[244:245], off offset:256
	s_mov_b32 s94, 0x10000
	v_lshl_add_u64 v[246:247], v[166:167], 0, s[94:95]
	global_load_dwordx4 v[184:187], v[246:247], off
	global_load_dwordx4 v[188:191], v[246:247], off offset:256
	s_mov_b32 s94, 0x18000
	v_lshl_add_u64 v[244:245], v[166:167], 0, s[94:95]
	global_load_dwordx4 v[192:195], v[244:245], off
	global_load_dwordx4 v[200:203], v[244:245], off offset:256
	s_mov_b32 s94, 0x40000
	v_lshl_add_u64 v[246:247], v[166:167], 0, s[94:95]
	global_load_dwordx4 v[204:207], v[246:247], off
	global_load_dwordx4 v[208:211], v[246:247], off offset:256
	s_mov_b32 s94, 0x48000
	v_lshl_add_u64 v[244:245], v[166:167], 0, s[94:95]
	global_load_dwordx4 v[212:215], v[244:245], off
	global_load_dwordx4 v[216:219], v[244:245], off offset:256
	s_mov_b32 s94, 0x50000
	v_lshl_add_u64 v[246:247], v[166:167], 0, s[94:95]
	global_load_dwordx4 v[228:231], v[246:247], off
	global_load_dwordx4 v[232:235], v[246:247], off offset:256
	s_mov_b32 s94, 0x58000
	v_lshl_add_u64 v[244:245], v[166:167], 0, s[94:95]
	global_load_dwordx4 v[236:239], v[244:245], off
	global_load_dwordx4 v[240:243], v[244:245], off offset:256
	v_and_b32_e32 v157, 64, v155
	v_xor_b32_e32 v156, 16, v155
	v_add_u32_e32 v157, 64, v157
	v_xor_b32_e32 v168, 32, v155
	v_cmp_lt_i32_e32 vcc, v156, v157
	s_waitcnt vmcnt(0)
	v_and_b32_e32 v169, 0xffff0000, v158
	v_cndmask_b32_e32 v156, v155, v156, vcc
	v_cmp_lt_i32_e32 vcc, v168, v157
	v_lshlrev_b32_e32 v172, 16, v162
	v_and_b32_e32 v173, 0xffff0000, v162
	v_cndmask_b32_e32 v157, v155, v168, vcc
	v_lshlrev_b32_e32 v168, 16, v158
	v_lshlrev_b32_e32 v158, 16, v159
	v_and_b32_e32 v159, 0xffff0000, v159
	v_lshlrev_b32_e32 v162, 16, v163
	v_and_b32_e32 v163, 0xffff0000, v163
	v_lshlrev_b32_e32 v170, 16, v160
	v_and_b32_e32 v171, 0xffff0000, v160
	v_lshlrev_b32_e32 v160, 16, v161
	v_and_b32_e32 v161, 0xffff0000, v161
	v_lshlrev_b32_e32 v174, 16, v164
	v_and_b32_e32 v175, 0xffff0000, v164
	v_lshlrev_b32_e32 v164, 16, v165
	v_and_b32_e32 v165, 0xffff0000, v165
	v_pk_add_f32 v[128:129], v[128:129], v[158:159]
	v_pk_add_f32 v[126:127], v[126:127], v[168:169]
	v_pk_add_f32 v[120:121], v[120:121], v[162:163]
	v_pk_add_f32 v[118:119], v[118:119], v[172:173]
	v_pk_add_f32 v[124:125], v[124:125], v[160:161]
	v_pk_add_f32 v[122:123], v[122:123], v[170:171]
	v_pk_add_f32 v[158:159], v[116:117], v[164:165]
	v_pk_add_f32 v[160:161], v[114:115], v[174:175]
	v_mul_f32_e32 v116, v127, v127
	v_mul_f32_e32 v117, v129, v129
	v_mul_f32_e32 v164, v119, v119
	v_mul_f32_e32 v165, v121, v121
	v_cvt_pk_bf16_f32 v114, v126, v127
	v_mul_f32_e32 v127, v123, v123
	v_mul_f32_e32 v163, v161, v161
	v_fmac_f32_e32 v116, v126, v126
	v_fmac_f32_e32 v117, v128, v128
	v_fmac_f32_e32 v164, v118, v118
	v_fmac_f32_e32 v165, v120, v120
	v_cvt_pk_bf16_f32 v115, v128, v129
	v_mul_f32_e32 v129, v125, v125
	v_mul_f32_e32 v162, v159, v159
	v_fmac_f32_e32 v127, v122, v122
	v_fmac_f32_e32 v163, v160, v160
	v_add_f32_e32 v116, v116, v117
	v_add_f32_e32 v117, v164, v165
	v_fmac_f32_e32 v129, v124, v124
	v_fmac_f32_e32 v162, v158, v158
	v_add_f32_e32 v116, v127, v116
	v_add_f32_e32 v117, v163, v117
	v_add_f32_e32 v116, v129, v116
	v_add_f32_e32 v117, v162, v117
	v_lshlrev_b32_e32 v156, 2, v156
	v_add_f32_e32 v126, v116, v117
	ds_bpermute_b32 v127, v156, v126
	v_cvt_pk_bf16_f32 v116, v122, v123
	v_cvt_pk_bf16_f32 v117, v124, v125
	global_store_dwordx4 v[166:167], v[114:117], off
	v_cvt_pk_bf16_f32 v118, v118, v119
	v_cvt_pk_bf16_f32 v119, v120, v121
	s_waitcnt lgkmcnt(0)
	v_add_f32_e32 v114, v126, v127
	v_lshlrev_b32_e32 v116, 2, v157
	ds_bpermute_b32 v115, v116, v114
	v_cvt_pk_bf16_f32 v120, v160, v161
	v_cvt_pk_bf16_f32 v121, v158, v159
	global_store_dwordx4 v[166:167], v[118:121], off offset:256
	s_and_saveexec_b64 s[12:13], s[2:3]
	s_cbranch_execz .LBB0_1574
	v_lshl_add_u64 v[118:119], v[148:149], 2, s[6:7]
	s_waitcnt lgkmcnt(0)
	v_add_f32_e32 v114, v114, v115
	global_atomic_add_f32 v[118:119], v114, off
.LBB0_1574:
	s_or_b64 exec, exec, s[12:13]
	v_or_b32_e32 v114, 16, v148
	s_waitcnt lgkmcnt(0)
	v_ashrrev_i32_e32 v115, 31, v114
	v_lshlrev_b64 v[118:119], 11, v[114:115]
	v_lshl_add_u64 v[118:119], s[78:79], 0, v[118:119]
	v_lshl_add_u64 v[126:127], v[146:147], 1, v[118:119]
	v_mov_b32_e32 v118, v176
	v_mov_b32_e32 v119, v177
	v_mov_b32_e32 v120, v178
	v_mov_b32_e32 v121, v179
	v_mov_b32_e32 v122, v180
	v_mov_b32_e32 v123, v181
	v_mov_b32_e32 v124, v182
	v_mov_b32_e32 v125, v183
	v_lshlrev_b32_e32 v128, 16, v118
	v_and_b32_e32 v129, 0xffff0000, v118
	v_lshlrev_b32_e32 v118, 16, v119
	v_and_b32_e32 v119, 0xffff0000, v119
	v_lshlrev_b32_e32 v160, 16, v122
	v_and_b32_e32 v161, 0xffff0000, v122
	v_lshlrev_b32_e32 v122, 16, v123
	v_and_b32_e32 v123, 0xffff0000, v123
	v_lshlrev_b32_e32 v158, 16, v120
	v_and_b32_e32 v159, 0xffff0000, v120
	v_lshlrev_b32_e32 v120, 16, v121
	v_and_b32_e32 v121, 0xffff0000, v121
	v_lshlrev_b32_e32 v162, 16, v124
	v_and_b32_e32 v163, 0xffff0000, v124
	v_lshlrev_b32_e32 v124, 16, v125
	v_and_b32_e32 v125, 0xffff0000, v125
	v_pk_add_f32 v[112:113], v[112:113], v[118:119]
	v_pk_add_f32 v[110:111], v[110:111], v[128:129]
	v_pk_add_f32 v[104:105], v[104:105], v[122:123]
	v_pk_add_f32 v[102:103], v[102:103], v[160:161]
	v_pk_add_f32 v[108:109], v[108:109], v[120:121]
	v_pk_add_f32 v[106:107], v[106:107], v[158:159]
	v_pk_add_f32 v[118:119], v[100:101], v[124:125]
	v_pk_add_f32 v[120:121], v[98:99], v[162:163]
	v_mul_f32_e32 v100, v111, v111
	v_mul_f32_e32 v101, v113, v113
	v_mul_f32_e32 v123, v103, v103
	v_mul_f32_e32 v124, v105, v105
	v_cvt_pk_bf16_f32 v98, v110, v111
	v_mul_f32_e32 v111, v107, v107
	v_mul_f32_e32 v122, v121, v121
	v_fmac_f32_e32 v100, v110, v110
	v_fmac_f32_e32 v101, v112, v112
	v_fmac_f32_e32 v123, v102, v102
	v_fmac_f32_e32 v124, v104, v104
	v_cvt_pk_bf16_f32 v99, v112, v113
	v_mul_f32_e32 v113, v109, v109
	v_mul_f32_e32 v117, v119, v119
	v_fmac_f32_e32 v111, v106, v106
	v_fmac_f32_e32 v122, v120, v120
	v_add_f32_e32 v100, v100, v101
	v_add_f32_e32 v101, v123, v124
	v_fmac_f32_e32 v113, v108, v108
	v_fmac_f32_e32 v117, v118, v118
	v_add_f32_e32 v100, v111, v100
	v_add_f32_e32 v101, v122, v101
	v_add_f32_e32 v100, v113, v100
	v_add_f32_e32 v101, v117, v101
	v_add_f32_e32 v110, v100, v101
	ds_bpermute_b32 v111, v156, v110
	v_cvt_pk_bf16_f32 v100, v106, v107
	v_cvt_pk_bf16_f32 v101, v108, v109
	global_store_dwordx4 v[126:127], v[98:101], off
	s_waitcnt lgkmcnt(0)
	s_nop 0
	v_add_f32_e32 v98, v110, v111
	ds_bpermute_b32 v99, v116, v98
	v_cvt_pk_bf16_f32 v100, v102, v103
	v_cvt_pk_bf16_f32 v101, v104, v105
	v_cvt_pk_bf16_f32 v102, v120, v121
	v_cvt_pk_bf16_f32 v103, v118, v119
	global_store_dwordx4 v[126:127], v[100:103], off offset:256
	s_and_saveexec_b64 s[12:13], s[2:3]
	s_cbranch_execz .LBB0_1576
	v_lshl_add_u64 v[100:101], v[114:115], 2, s[6:7]
	s_waitcnt lgkmcnt(0)
	v_add_f32_e32 v98, v98, v99
	global_atomic_add_f32 v[100:101], v98, off
.LBB0_1576:
	s_or_b64 exec, exec, s[12:13]
	v_or_b32_e32 v98, 32, v148
	s_waitcnt lgkmcnt(0)
	v_ashrrev_i32_e32 v99, 31, v98
	v_lshlrev_b64 v[100:101], 11, v[98:99]
	v_lshl_add_u64 v[100:101], s[78:79], 0, v[100:101]
	v_lshl_add_u64 v[108:109], v[146:147], 1, v[100:101]
	v_mov_b32_e32 v100, v184
	v_mov_b32_e32 v101, v185
	v_mov_b32_e32 v102, v186
	v_mov_b32_e32 v103, v187
	v_mov_b32_e32 v104, v188
	v_mov_b32_e32 v105, v189
	v_mov_b32_e32 v106, v190
	v_mov_b32_e32 v107, v191
	v_lshlrev_b32_e32 v110, 16, v100
	v_and_b32_e32 v111, 0xffff0000, v100
	v_lshlrev_b32_e32 v100, 16, v101
	v_and_b32_e32 v101, 0xffff0000, v101
	v_lshlrev_b32_e32 v114, 16, v104
	v_and_b32_e32 v115, 0xffff0000, v104
	v_lshlrev_b32_e32 v104, 16, v105
	v_and_b32_e32 v105, 0xffff0000, v105
	v_lshlrev_b32_e32 v112, 16, v102
	v_and_b32_e32 v113, 0xffff0000, v102
	v_lshlrev_b32_e32 v102, 16, v103
	v_and_b32_e32 v103, 0xffff0000, v103
	v_lshlrev_b32_e32 v118, 16, v106
	v_and_b32_e32 v119, 0xffff0000, v106
	v_lshlrev_b32_e32 v106, 16, v107
	v_and_b32_e32 v107, 0xffff0000, v107
	v_pk_add_f32 v[96:97], v[96:97], v[100:101]
	v_pk_add_f32 v[94:95], v[94:95], v[110:111]
	v_pk_add_f32 v[88:89], v[88:89], v[104:105]
	v_pk_add_f32 v[86:87], v[86:87], v[114:115]
	v_pk_add_f32 v[92:93], v[92:93], v[102:103]
	v_pk_add_f32 v[90:91], v[90:91], v[112:113]
	v_pk_add_f32 v[100:101], v[84:85], v[106:107]
	v_pk_add_f32 v[102:103], v[82:83], v[118:119]
	v_mul_f32_e32 v84, v95, v95
	v_mul_f32_e32 v85, v97, v97
	v_mul_f32_e32 v106, v87, v87
	v_mul_f32_e32 v107, v89, v89
	v_cvt_pk_bf16_f32 v82, v94, v95
	v_mul_f32_e32 v95, v91, v91
	v_mul_f32_e32 v105, v103, v103
	v_fmac_f32_e32 v84, v94, v94
	v_fmac_f32_e32 v85, v96, v96
	v_fmac_f32_e32 v106, v86, v86
	v_fmac_f32_e32 v107, v88, v88
	v_cvt_pk_bf16_f32 v83, v96, v97
	v_mul_f32_e32 v97, v93, v93
	v_mul_f32_e32 v104, v101, v101
	v_fmac_f32_e32 v95, v90, v90
	v_fmac_f32_e32 v105, v102, v102
	v_add_f32_e32 v84, v84, v85
	v_add_f32_e32 v85, v106, v107
	v_fmac_f32_e32 v97, v92, v92
	v_fmac_f32_e32 v104, v100, v100
	v_add_f32_e32 v84, v95, v84
	v_add_f32_e32 v85, v105, v85
	v_add_f32_e32 v84, v97, v84
	v_add_f32_e32 v85, v104, v85
	v_add_f32_e32 v94, v84, v85
	ds_bpermute_b32 v95, v156, v94
	v_cvt_pk_bf16_f32 v84, v90, v91
	v_cvt_pk_bf16_f32 v85, v92, v93
	global_store_dwordx4 v[108:109], v[82:85], off
	s_waitcnt lgkmcnt(0)
	s_nop 0
	v_add_f32_e32 v82, v94, v95
	ds_bpermute_b32 v83, v116, v82
	v_cvt_pk_bf16_f32 v84, v86, v87
	v_cvt_pk_bf16_f32 v85, v88, v89
	v_cvt_pk_bf16_f32 v86, v102, v103
	v_cvt_pk_bf16_f32 v87, v100, v101
	global_store_dwordx4 v[108:109], v[84:87], off offset:256
	s_and_saveexec_b64 s[12:13], s[2:3]
	s_cbranch_execz .LBB0_1578
	v_lshl_add_u64 v[84:85], v[98:99], 2, s[6:7]
	s_waitcnt lgkmcnt(0)
	v_add_f32_e32 v82, v82, v83
	global_atomic_add_f32 v[84:85], v82, off
.LBB0_1578:
	s_or_b64 exec, exec, s[12:13]
	v_or_b32_e32 v82, 48, v148
	s_waitcnt lgkmcnt(0)
	v_ashrrev_i32_e32 v83, 31, v82
	v_lshlrev_b64 v[84:85], 11, v[82:83]
	v_lshl_add_u64 v[84:85], s[78:79], 0, v[84:85]
	v_lshl_add_u64 v[92:93], v[146:147], 1, v[84:85]
	v_mov_b32_e32 v84, v192
	v_mov_b32_e32 v85, v193
	v_mov_b32_e32 v86, v194
	v_mov_b32_e32 v87, v195
	v_mov_b32_e32 v88, v200
	v_mov_b32_e32 v89, v201
	v_mov_b32_e32 v90, v202
	v_mov_b32_e32 v91, v203
	v_lshlrev_b32_e32 v94, 16, v84
	v_and_b32_e32 v95, 0xffff0000, v84
	v_lshlrev_b32_e32 v84, 16, v85
	v_and_b32_e32 v85, 0xffff0000, v85
	v_lshlrev_b32_e32 v98, 16, v88
	v_and_b32_e32 v99, 0xffff0000, v88
	v_lshlrev_b32_e32 v88, 16, v89
	v_and_b32_e32 v89, 0xffff0000, v89
	v_lshlrev_b32_e32 v96, 16, v86
	v_and_b32_e32 v97, 0xffff0000, v86
	v_lshlrev_b32_e32 v86, 16, v87
	v_and_b32_e32 v87, 0xffff0000, v87
	v_lshlrev_b32_e32 v100, 16, v90
	v_and_b32_e32 v101, 0xffff0000, v90
	v_lshlrev_b32_e32 v90, 16, v91
	v_and_b32_e32 v91, 0xffff0000, v91
	v_pk_add_f32 v[80:81], v[80:81], v[84:85]
	v_pk_add_f32 v[78:79], v[78:79], v[94:95]
	v_pk_add_f32 v[72:73], v[72:73], v[88:89]
	v_pk_add_f32 v[70:71], v[70:71], v[98:99]
	v_pk_add_f32 v[76:77], v[76:77], v[86:87]
	v_pk_add_f32 v[74:75], v[74:75], v[96:97]
	v_pk_add_f32 v[84:85], v[68:69], v[90:91]
	v_pk_add_f32 v[86:87], v[66:67], v[100:101]
	v_mul_f32_e32 v68, v79, v79
	v_mul_f32_e32 v69, v81, v81
	v_mul_f32_e32 v90, v71, v71
	v_mul_f32_e32 v91, v73, v73
	v_cvt_pk_bf16_f32 v66, v78, v79
	v_mul_f32_e32 v79, v75, v75
	v_mul_f32_e32 v89, v87, v87
	v_fmac_f32_e32 v68, v78, v78
	v_fmac_f32_e32 v69, v80, v80
	v_fmac_f32_e32 v90, v70, v70
	v_fmac_f32_e32 v91, v72, v72
	v_cvt_pk_bf16_f32 v67, v80, v81
	v_mul_f32_e32 v81, v77, v77
	v_mul_f32_e32 v88, v85, v85
	v_fmac_f32_e32 v79, v74, v74
	v_fmac_f32_e32 v89, v86, v86
	v_add_f32_e32 v68, v68, v69
	v_add_f32_e32 v69, v90, v91
	v_fmac_f32_e32 v81, v76, v76
	v_fmac_f32_e32 v88, v84, v84
	v_add_f32_e32 v68, v79, v68
	v_add_f32_e32 v69, v89, v69
	v_add_f32_e32 v68, v81, v68
	v_add_f32_e32 v69, v88, v69
	v_add_f32_e32 v78, v68, v69
	ds_bpermute_b32 v79, v156, v78
	v_cvt_pk_bf16_f32 v68, v74, v75
	v_cvt_pk_bf16_f32 v69, v76, v77
	global_store_dwordx4 v[92:93], v[66:69], off
	s_waitcnt lgkmcnt(0)
	s_nop 0
	v_add_f32_e32 v66, v78, v79
	ds_bpermute_b32 v67, v116, v66
	v_cvt_pk_bf16_f32 v68, v70, v71
	v_cvt_pk_bf16_f32 v69, v72, v73
	v_cvt_pk_bf16_f32 v70, v86, v87
	v_cvt_pk_bf16_f32 v71, v84, v85
	global_store_dwordx4 v[92:93], v[68:71], off offset:256
	s_and_saveexec_b64 s[12:13], s[2:3]
	s_cbranch_execz .LBB0_1580
	v_lshl_add_u64 v[68:69], v[82:83], 2, s[6:7]
	s_waitcnt lgkmcnt(0)
	v_add_f32_e32 v66, v66, v67
	global_atomic_add_f32 v[68:69], v66, off
.LBB0_1580:
	s_or_b64 exec, exec, s[12:13]
	v_add_u32_e32 v66, 0x80, v148
	s_waitcnt lgkmcnt(0)
	v_ashrrev_i32_e32 v67, 31, v66
	v_lshlrev_b64 v[68:69], 11, v[66:67]
	v_lshl_add_u64 v[68:69], s[78:79], 0, v[68:69]
	v_lshl_add_u64 v[76:77], v[146:147], 1, v[68:69]
	v_mov_b32_e32 v68, v204
	v_mov_b32_e32 v69, v205
	v_mov_b32_e32 v70, v206
	v_mov_b32_e32 v71, v207
	v_mov_b32_e32 v72, v208
	v_mov_b32_e32 v73, v209
	v_mov_b32_e32 v74, v210
	v_mov_b32_e32 v75, v211
	v_lshlrev_b32_e32 v78, 16, v68
	v_and_b32_e32 v79, 0xffff0000, v68
	v_lshlrev_b32_e32 v68, 16, v69
	v_and_b32_e32 v69, 0xffff0000, v69
	v_lshlrev_b32_e32 v82, 16, v72
	v_and_b32_e32 v83, 0xffff0000, v72
	v_lshlrev_b32_e32 v72, 16, v73
	v_and_b32_e32 v73, 0xffff0000, v73
	v_lshlrev_b32_e32 v80, 16, v70
	v_and_b32_e32 v81, 0xffff0000, v70
	v_lshlrev_b32_e32 v70, 16, v71
	v_and_b32_e32 v71, 0xffff0000, v71
	v_lshlrev_b32_e32 v84, 16, v74
	v_and_b32_e32 v85, 0xffff0000, v74
	v_lshlrev_b32_e32 v74, 16, v75
	v_and_b32_e32 v75, 0xffff0000, v75
	v_pk_add_f32 v[64:65], v[64:65], v[68:69]
	v_pk_add_f32 v[62:63], v[62:63], v[78:79]
	v_pk_add_f32 v[56:57], v[56:57], v[72:73]
	v_pk_add_f32 v[54:55], v[54:55], v[82:83]
	v_pk_add_f32 v[60:61], v[60:61], v[70:71]
	v_pk_add_f32 v[58:59], v[58:59], v[80:81]
	v_pk_add_f32 v[68:69], v[52:53], v[74:75]
	v_pk_add_f32 v[70:71], v[50:51], v[84:85]
	v_mul_f32_e32 v52, v63, v63
	v_mul_f32_e32 v53, v65, v65
	v_mul_f32_e32 v74, v55, v55
	v_mul_f32_e32 v75, v57, v57
	v_cvt_pk_bf16_f32 v50, v62, v63
	v_mul_f32_e32 v63, v59, v59
	v_mul_f32_e32 v73, v71, v71
	v_fmac_f32_e32 v52, v62, v62
	v_fmac_f32_e32 v53, v64, v64
	v_fmac_f32_e32 v74, v54, v54
	v_fmac_f32_e32 v75, v56, v56
	v_cvt_pk_bf16_f32 v51, v64, v65
	v_mul_f32_e32 v65, v61, v61
	v_mul_f32_e32 v72, v69, v69
	v_fmac_f32_e32 v63, v58, v58
	v_fmac_f32_e32 v73, v70, v70
	v_add_f32_e32 v52, v52, v53
	v_add_f32_e32 v53, v74, v75
	v_fmac_f32_e32 v65, v60, v60
	v_fmac_f32_e32 v72, v68, v68
	v_add_f32_e32 v52, v63, v52
	v_add_f32_e32 v53, v73, v53
	v_add_f32_e32 v52, v65, v52
	v_add_f32_e32 v53, v72, v53
	v_add_f32_e32 v62, v52, v53
	ds_bpermute_b32 v63, v156, v62
	v_cvt_pk_bf16_f32 v52, v58, v59
	v_cvt_pk_bf16_f32 v53, v60, v61
	global_store_dwordx4 v[76:77], v[50:53], off
	s_waitcnt lgkmcnt(0)
	s_nop 0
	v_add_f32_e32 v50, v62, v63
	ds_bpermute_b32 v51, v116, v50
	v_cvt_pk_bf16_f32 v52, v54, v55
	v_cvt_pk_bf16_f32 v53, v56, v57
	v_cvt_pk_bf16_f32 v54, v70, v71
	v_cvt_pk_bf16_f32 v55, v68, v69
	global_store_dwordx4 v[76:77], v[52:55], off offset:256
	s_and_saveexec_b64 s[12:13], s[2:3]
	s_cbranch_execz .LBB0_1582
	v_lshl_add_u64 v[52:53], v[66:67], 2, s[6:7]
	s_waitcnt lgkmcnt(0)
	v_add_f32_e32 v50, v50, v51
	global_atomic_add_f32 v[52:53], v50, off
.LBB0_1582:
	s_or_b64 exec, exec, s[12:13]
	v_add_u32_e32 v50, 0x90, v148
	s_waitcnt lgkmcnt(0)
	v_ashrrev_i32_e32 v51, 31, v50
	v_lshlrev_b64 v[52:53], 11, v[50:51]
	v_lshl_add_u64 v[52:53], s[78:79], 0, v[52:53]
	v_lshl_add_u64 v[60:61], v[146:147], 1, v[52:53]
	v_mov_b32_e32 v52, v212
	v_mov_b32_e32 v53, v213
	v_mov_b32_e32 v54, v214
	v_mov_b32_e32 v55, v215
	v_mov_b32_e32 v56, v216
	v_mov_b32_e32 v57, v217
	v_mov_b32_e32 v58, v218
	v_mov_b32_e32 v59, v219
	v_lshlrev_b32_e32 v62, 16, v52
	v_and_b32_e32 v63, 0xffff0000, v52
	v_lshlrev_b32_e32 v52, 16, v53
	v_and_b32_e32 v53, 0xffff0000, v53
	v_lshlrev_b32_e32 v66, 16, v56
	v_and_b32_e32 v67, 0xffff0000, v56
	v_lshlrev_b32_e32 v56, 16, v57
	v_and_b32_e32 v57, 0xffff0000, v57
	v_lshlrev_b32_e32 v64, 16, v54
	v_and_b32_e32 v65, 0xffff0000, v54
	v_lshlrev_b32_e32 v54, 16, v55
	v_and_b32_e32 v55, 0xffff0000, v55
	v_lshlrev_b32_e32 v68, 16, v58
	v_and_b32_e32 v69, 0xffff0000, v58
	v_lshlrev_b32_e32 v58, 16, v59
	v_and_b32_e32 v59, 0xffff0000, v59
	v_pk_add_f32 v[48:49], v[48:49], v[52:53]
	v_pk_add_f32 v[46:47], v[46:47], v[62:63]
	v_pk_add_f32 v[40:41], v[40:41], v[56:57]
	v_pk_add_f32 v[38:39], v[38:39], v[66:67]
	v_pk_add_f32 v[44:45], v[44:45], v[54:55]
	v_pk_add_f32 v[42:43], v[42:43], v[64:65]
	v_pk_add_f32 v[52:53], v[36:37], v[58:59]
	v_pk_add_f32 v[54:55], v[34:35], v[68:69]
	v_mul_f32_e32 v36, v47, v47
	v_mul_f32_e32 v37, v49, v49
	v_mul_f32_e32 v58, v39, v39
	v_mul_f32_e32 v59, v41, v41
	v_cvt_pk_bf16_f32 v34, v46, v47
	v_mul_f32_e32 v47, v43, v43
	v_mul_f32_e32 v57, v55, v55
	v_fmac_f32_e32 v36, v46, v46
	v_fmac_f32_e32 v37, v48, v48
	v_fmac_f32_e32 v58, v38, v38
	v_fmac_f32_e32 v59, v40, v40
	v_cvt_pk_bf16_f32 v35, v48, v49
	v_mul_f32_e32 v49, v45, v45
	v_mul_f32_e32 v56, v53, v53
	v_fmac_f32_e32 v47, v42, v42
	v_fmac_f32_e32 v57, v54, v54
	v_add_f32_e32 v36, v36, v37
	v_add_f32_e32 v37, v58, v59
	v_fmac_f32_e32 v49, v44, v44
	v_fmac_f32_e32 v56, v52, v52
	v_add_f32_e32 v36, v47, v36
	v_add_f32_e32 v37, v57, v37
	v_add_f32_e32 v36, v49, v36
	v_add_f32_e32 v37, v56, v37
	v_add_f32_e32 v46, v36, v37
	ds_bpermute_b32 v47, v156, v46
	v_cvt_pk_bf16_f32 v36, v42, v43
	v_cvt_pk_bf16_f32 v37, v44, v45
	global_store_dwordx4 v[60:61], v[34:37], off
	s_waitcnt lgkmcnt(0)
	s_nop 0
	v_add_f32_e32 v34, v46, v47
	ds_bpermute_b32 v35, v116, v34
	v_cvt_pk_bf16_f32 v36, v38, v39
	v_cvt_pk_bf16_f32 v37, v40, v41
	v_cvt_pk_bf16_f32 v38, v54, v55
	v_cvt_pk_bf16_f32 v39, v52, v53
	global_store_dwordx4 v[60:61], v[36:39], off offset:256
	s_and_saveexec_b64 s[12:13], s[2:3]
	s_cbranch_execz .LBB0_1584
	v_lshl_add_u64 v[36:37], v[50:51], 2, s[6:7]
	s_waitcnt lgkmcnt(0)
	v_add_f32_e32 v34, v34, v35
	global_atomic_add_f32 v[36:37], v34, off
.LBB0_1584:
	s_or_b64 exec, exec, s[12:13]
	v_add_u32_e32 v34, 0xa0, v148
	s_waitcnt lgkmcnt(0)
	v_ashrrev_i32_e32 v35, 31, v34
	v_lshlrev_b64 v[36:37], 11, v[34:35]
	v_lshl_add_u64 v[36:37], s[78:79], 0, v[36:37]
	v_lshl_add_u64 v[44:45], v[146:147], 1, v[36:37]
	v_mov_b32_e32 v36, v228
	v_mov_b32_e32 v37, v229
	v_mov_b32_e32 v38, v230
	v_mov_b32_e32 v39, v231
	v_mov_b32_e32 v40, v232
	v_mov_b32_e32 v41, v233
	v_mov_b32_e32 v42, v234
	v_mov_b32_e32 v43, v235
	v_lshlrev_b32_e32 v46, 16, v36
	v_and_b32_e32 v47, 0xffff0000, v36
	v_lshlrev_b32_e32 v36, 16, v37
	v_and_b32_e32 v37, 0xffff0000, v37
	v_lshlrev_b32_e32 v50, 16, v40
	v_and_b32_e32 v51, 0xffff0000, v40
	v_lshlrev_b32_e32 v40, 16, v41
	v_and_b32_e32 v41, 0xffff0000, v41
	v_lshlrev_b32_e32 v48, 16, v38
	v_and_b32_e32 v49, 0xffff0000, v38
	v_lshlrev_b32_e32 v38, 16, v39
	v_and_b32_e32 v39, 0xffff0000, v39
	v_lshlrev_b32_e32 v52, 16, v42
	v_and_b32_e32 v53, 0xffff0000, v42
	v_lshlrev_b32_e32 v42, 16, v43
	v_and_b32_e32 v43, 0xffff0000, v43
	v_pk_add_f32 v[32:33], v[32:33], v[36:37]
	v_pk_add_f32 v[30:31], v[30:31], v[46:47]
	v_pk_add_f32 v[24:25], v[24:25], v[40:41]
	v_pk_add_f32 v[22:23], v[22:23], v[50:51]
	v_pk_add_f32 v[28:29], v[28:29], v[38:39]
	v_pk_add_f32 v[26:27], v[26:27], v[48:49]
	v_pk_add_f32 v[36:37], v[20:21], v[42:43]
	v_pk_add_f32 v[38:39], v[18:19], v[52:53]
	v_mul_f32_e32 v20, v31, v31
	v_mul_f32_e32 v21, v33, v33
	v_mul_f32_e32 v42, v23, v23
	v_mul_f32_e32 v43, v25, v25
	v_cvt_pk_bf16_f32 v18, v30, v31
	v_mul_f32_e32 v31, v27, v27
	v_mul_f32_e32 v41, v39, v39
	v_fmac_f32_e32 v20, v30, v30
	v_fmac_f32_e32 v21, v32, v32
	v_fmac_f32_e32 v42, v22, v22
	v_fmac_f32_e32 v43, v24, v24
	v_cvt_pk_bf16_f32 v19, v32, v33
	v_mul_f32_e32 v33, v29, v29
	v_mul_f32_e32 v40, v37, v37
	v_fmac_f32_e32 v31, v26, v26
	v_fmac_f32_e32 v41, v38, v38
	v_add_f32_e32 v20, v20, v21
	v_add_f32_e32 v21, v42, v43
	v_fmac_f32_e32 v33, v28, v28
	v_fmac_f32_e32 v40, v36, v36
	v_add_f32_e32 v20, v31, v20
	v_add_f32_e32 v21, v41, v21
	v_add_f32_e32 v20, v33, v20
	v_add_f32_e32 v21, v40, v21
	v_add_f32_e32 v30, v20, v21
	ds_bpermute_b32 v31, v156, v30
	v_cvt_pk_bf16_f32 v20, v26, v27
	v_cvt_pk_bf16_f32 v21, v28, v29
	global_store_dwordx4 v[44:45], v[18:21], off
	s_waitcnt lgkmcnt(0)
	s_nop 0
	v_add_f32_e32 v18, v30, v31
	ds_bpermute_b32 v19, v116, v18
	v_cvt_pk_bf16_f32 v20, v22, v23
	v_cvt_pk_bf16_f32 v21, v24, v25
	v_cvt_pk_bf16_f32 v22, v38, v39
	v_cvt_pk_bf16_f32 v23, v36, v37
	global_store_dwordx4 v[44:45], v[20:23], off offset:256
	s_and_saveexec_b64 s[12:13], s[2:3]
	s_cbranch_execz .LBB0_1586
	v_lshl_add_u64 v[20:21], v[34:35], 2, s[6:7]
	s_waitcnt lgkmcnt(0)
	v_add_f32_e32 v18, v18, v19
	global_atomic_add_f32 v[20:21], v18, off
.LBB0_1586:
	s_or_b64 exec, exec, s[12:13]
	v_add_u32_e32 v18, 0xb0, v148
	s_waitcnt lgkmcnt(0)
	v_ashrrev_i32_e32 v19, 31, v18
	v_lshlrev_b64 v[20:21], 11, v[18:19]
	v_lshl_add_u64 v[20:21], s[78:79], 0, v[20:21]
	v_lshl_add_u64 v[28:29], v[146:147], 1, v[20:21]
	v_mov_b32_e32 v20, v236
	v_mov_b32_e32 v21, v237
	v_mov_b32_e32 v22, v238
	v_mov_b32_e32 v23, v239
	v_mov_b32_e32 v24, v240
	v_mov_b32_e32 v25, v241
	v_mov_b32_e32 v26, v242
	v_mov_b32_e32 v27, v243
	v_lshlrev_b32_e32 v30, 16, v20
	v_and_b32_e32 v31, 0xffff0000, v20
	v_lshlrev_b32_e32 v20, 16, v21
	v_and_b32_e32 v21, 0xffff0000, v21
	v_lshlrev_b32_e32 v34, 16, v24
	v_and_b32_e32 v35, 0xffff0000, v24
	v_lshlrev_b32_e32 v24, 16, v25
	v_and_b32_e32 v25, 0xffff0000, v25
	v_lshlrev_b32_e32 v32, 16, v22
	v_and_b32_e32 v33, 0xffff0000, v22
	v_lshlrev_b32_e32 v22, 16, v23
	v_and_b32_e32 v23, 0xffff0000, v23
	v_lshlrev_b32_e32 v36, 16, v26
	v_and_b32_e32 v37, 0xffff0000, v26
	v_lshlrev_b32_e32 v26, 16, v27
	v_and_b32_e32 v27, 0xffff0000, v27
	v_pk_add_f32 v[16:17], v[16:17], v[20:21]
	v_pk_add_f32 v[14:15], v[14:15], v[30:31]
	v_pk_add_f32 v[8:9], v[8:9], v[24:25]
	v_pk_add_f32 v[6:7], v[6:7], v[34:35]
	v_pk_add_f32 v[12:13], v[12:13], v[22:23]
	v_pk_add_f32 v[10:11], v[10:11], v[32:33]
	v_pk_add_f32 v[20:21], v[4:5], v[26:27]
	v_pk_add_f32 v[22:23], v[2:3], v[36:37]
	v_mul_f32_e32 v4, v15, v15
	v_mul_f32_e32 v5, v17, v17
	v_mul_f32_e32 v26, v7, v7
	v_mul_f32_e32 v27, v9, v9
	v_cvt_pk_bf16_f32 v2, v14, v15
	v_mul_f32_e32 v15, v11, v11
	v_mul_f32_e32 v25, v23, v23
	v_fmac_f32_e32 v4, v14, v14
	v_fmac_f32_e32 v5, v16, v16
	v_fmac_f32_e32 v26, v6, v6
	v_fmac_f32_e32 v27, v8, v8
	v_cvt_pk_bf16_f32 v3, v16, v17
	v_mul_f32_e32 v17, v13, v13
	v_mul_f32_e32 v24, v21, v21
	v_fmac_f32_e32 v15, v10, v10
	v_fmac_f32_e32 v25, v22, v22
	v_add_f32_e32 v4, v4, v5
	v_add_f32_e32 v5, v26, v27
	v_fmac_f32_e32 v17, v12, v12
	v_fmac_f32_e32 v24, v20, v20
	v_add_f32_e32 v4, v15, v4
	v_add_f32_e32 v5, v25, v5
	v_add_f32_e32 v4, v17, v4
	v_add_f32_e32 v5, v24, v5
	v_add_f32_e32 v14, v4, v5
	ds_bpermute_b32 v15, v156, v14
	v_cvt_pk_bf16_f32 v4, v10, v11
	v_cvt_pk_bf16_f32 v5, v12, v13
	global_store_dwordx4 v[28:29], v[2:5], off
	s_waitcnt lgkmcnt(0)
	s_nop 0
	v_add_f32_e32 v2, v14, v15
	ds_bpermute_b32 v3, v116, v2
	v_cvt_pk_bf16_f32 v4, v6, v7
	v_cvt_pk_bf16_f32 v5, v8, v9
	v_cvt_pk_bf16_f32 v6, v22, v23
	v_cvt_pk_bf16_f32 v7, v20, v21
	global_store_dwordx4 v[28:29], v[4:7], off offset:256
	s_and_saveexec_b64 s[12:13], s[2:3]
	s_cbranch_execz .LBB0_1588
	v_lshl_add_u64 v[4:5], v[18:19], 2, s[6:7]
	s_waitcnt lgkmcnt(0)
	v_add_f32_e32 v2, v2, v3
	global_atomic_add_f32 v[4:5], v2, off
